# stack: + DPP wave sums, batched phase-9 sample epilogue, phase-5 sample-row scale/shift loads issued together
# baseline (speedup 1.0000x reference)
.LBB0_251:
	s_waitcnt vmcnt(3)
	v_pk_mul_f32 v[116:117], v[62:63], v[62:63]
	v_pk_mul_f32 v[118:119], v[60:61], v[60:61]
	s_waitcnt vmcnt(2)
	v_pk_mul_f32 v[112:113], v[58:59], v[58:59]
	v_pk_mul_f32 v[114:115], v[56:57], v[56:57]
	v_pk_mov_b32 v[120:121], v[118:119], v[116:117] op_sel:[1,0]
	v_mov_b32_e32 v119, v117
	v_pk_add_f32 v[116:117], v[120:121], v[118:119]
	v_pk_mov_b32 v[118:119], v[114:115], v[112:113] op_sel:[1,0]
	v_mov_b32_e32 v115, v113
	v_pk_add_f32 v[112:113], v[118:119], v[114:115]
	v_pk_add_f32 v[116:117], v[116:117], v[116:117] op_sel_hi:[0,1]
	v_pk_add_f32 v[112:113], v[112:113], v[112:113] op_sel_hi:[0,1]
	s_waitcnt vmcnt(1)
	v_mul_f32_e32 v112, v44, v44
	v_pk_fma_f32 v[114:115], v[44:45], v[44:45], v[112:113] op_sel_hi:[1,1,0]
	v_mul_f32_e32 v112, v46, v46
	v_pk_fma_f32 v[118:119], v[46:47], v[46:47], v[112:113] op_sel_hi:[1,1,0]
	s_waitcnt vmcnt(0)
	v_mul_f32_e32 v114, v36, v36
	v_mul_f32_e32 v118, v37, v37
	v_mul_f32_e32 v116, v38, v38
	v_mul_f32_e32 v112, v39, v39
	v_pk_add_f32 v[114:115], v[114:115], v[118:119]
	v_pk_add_f32 v[112:113], v[116:117], v[112:113]
	s_add_u32 s50, s50, 0x1000
	v_pk_add_f32 v[112:113], v[114:115], v[112:113]
	s_addc_u32 s51, s51, 0
	v_add_f32_e32 v81, v112, v113
	s_add_u32 s48, s48, 0x400
	s_addc_u32 s49, s49, 0
	s_cmpk_lg_u32 s50, 0x8000
	s_nop 1
	v_add_f32_dpp v81, v81, v81 quad_perm:[1,0,3,2] row_mask:0xf bank_mask:0xf
	s_nop 1
	v_add_f32_dpp v81, v81, v81 quad_perm:[2,3,0,1] row_mask:0xf bank_mask:0xf
	s_nop 1
	v_add_f32_dpp v81, v81, v81 row_half_mirror row_mask:0xf bank_mask:0xf
	s_nop 1
	v_add_f32_dpp v81, v81, v81 row_ror:8 row_mask:0xf bank_mask:0xf
	v_mov_b32_e32 v111, v81
	s_nop 1
	v_permlane16_swap_b32_e32 v111, v81
	v_add_f32_e32 v81, v81, v111
	v_mov_b32_e32 v111, v81
	s_nop 1
	v_permlane32_swap_b32_e32 v111, v81
	v_add_f32_e32 v81, v81, v111
	v_fmamk_f32 v81, v81, 0x3a800000, v75
	v_mul_f32_e32 v111, 0x4f800000, v81
	v_cmp_gt_f32_e32 vcc, s8, v81
	s_nop 1
	v_cndmask_b32_e32 v81, v81, v111, vcc
	v_sqrt_f32_e32 v111, v81
	s_nop 0
	v_add_u32_e32 v112, -1, v111
	v_add_u32_e32 v113, 1, v111
	v_fma_f32 v114, -v112, v111, v81
	v_fma_f32 v115, -v113, v111, v81
	v_cmp_ge_f32_e64 s[0:1], 0, v114
	s_nop 1
	v_cndmask_b32_e64 v111, v111, v112, s[0:1]
	v_cmp_lt_f32_e64 s[0:1], 0, v115
	s_nop 1
	v_cndmask_b32_e64 v111, v111, v113, s[0:1]
	v_mul_f32_e32 v112, 0x37800000, v111
	v_cndmask_b32_e32 v111, v111, v112, vcc
	v_cmp_class_f32_e32 vcc, v81, v109
	v_lshl_add_u64 v[112:113], s[6:7], 1, v[86:87]
	s_nop 0
	v_cndmask_b32_e32 v81, v111, v81, vcc
	v_div_scale_f32 v111, s[0:1], v81, v81, 1.0
	v_rcp_f32_e32 v114, v111
	v_div_scale_f32 v115, vcc, 1.0, v81, 1.0
	v_fma_f32 v116, -v111, v114, 1.0
	v_fmac_f32_e32 v114, v116, v114
	v_mul_f32_e32 v116, v115, v114
	v_fma_f32 v117, -v111, v116, v115
	v_fmac_f32_e32 v116, v117, v114
	v_fma_f32 v111, -v111, v116, v115
	v_div_fmas_f32 v111, v111, v114, v116
	v_div_fixup_f32 v114, v111, v81, 1.0
	v_pk_mul_f32 v[60:61], v[60:61], v[114:115] op_sel_hi:[1,0]
	v_pk_mul_f32 v[56:57], v[56:57], v[114:115] op_sel_hi:[1,0]
	v_pk_mul_f32 v[44:45], v[44:45], v[114:115] op_sel_hi:[1,0]
	v_pk_mul_f32 v[36:37], v[36:37], v[114:115] op_sel_hi:[1,0]
	v_pk_mul_f32 v[62:63], v[62:63], v[114:115] op_sel_hi:[1,0]
	v_pk_fma_f32 v[60:61], v[90:91], v[60:61], v[16:17]
	v_pk_mul_f32 v[58:59], v[58:59], v[114:115] op_sel_hi:[1,0]
	v_pk_fma_f32 v[56:57], v[94:95], v[56:57], v[20:21]
	v_pk_mul_f32 v[46:47], v[46:47], v[114:115] op_sel_hi:[1,0]
	v_pk_fma_f32 v[44:45], v[98:99], v[44:45], v[24:25]
	v_pk_mul_f32 v[38:39], v[38:39], v[114:115] op_sel_hi:[1,0]
	v_pk_fma_f32 v[36:37], v[102:103], v[36:37], v[28:29]
	v_pk_fma_f32 v[62:63], v[88:89], v[62:63], v[18:19]
	v_cvt_pk_bf16_f32 v60, v60, v61
	v_pk_fma_f32 v[58:59], v[92:93], v[58:59], v[22:23]
	v_cvt_pk_bf16_f32 v61, v62, v63
	global_store_dwordx2 v[112:113], v[60:61], off
	v_cvt_pk_bf16_f32 v56, v56, v57
	v_cvt_pk_bf16_f32 v57, v58, v59
	global_store_dwordx2 v[112:113], v[56:57], off offset:512
	v_pk_fma_f32 v[46:47], v[96:97], v[46:47], v[26:27]
	v_cvt_pk_bf16_f32 v44, v44, v45
	v_pk_fma_f32 v[38:39], v[100:101], v[38:39], v[30:31]
	v_cvt_pk_bf16_f32 v45, v46, v47
	global_store_dwordx2 v[112:113], v[44:45], off offset:1024
	v_cvt_pk_bf16_f32 v36, v36, v37
	v_cvt_pk_bf16_f32 v37, v38, v39
	global_store_dwordx2 v[112:113], v[36:37], off offset:1536
	v_mov_b32_e32 v60, v32
	v_mov_b32_e32 v61, v33
	v_mov_b32_e32 v62, v34
	v_mov_b32_e32 v63, v35
	v_mov_b32_e32 v56, v40
	v_mov_b32_e32 v57, v41
	v_mov_b32_e32 v58, v42
	v_mov_b32_e32 v59, v43
	v_mov_b32_e32 v44, v48
	v_mov_b32_e32 v45, v49
	v_mov_b32_e32 v46, v50
	v_mov_b32_e32 v47, v51
	v_mov_b32_e32 v36, v52
	v_mov_b32_e32 v37, v53
	v_mov_b32_e32 v38, v54
	v_mov_b32_e32 v39, v55
	s_cbranch_scc0 .LBB0_249

.LBB0_256:
	global_load_dwordx4 v[38:41], v[26:27], off
	global_load_dwordx4 v[42:45], v[26:27], off offset:1024
	global_load_dwordx4 v[16:19], v[26:27], off offset:3072
	global_load_dwordx4 v[20:23], v[26:27], off offset:2048
	v_ashrrev_i32_e32 v47, 2, v64
	v_add_u32_e32 v46, 0x4000, v64
	v_add_u32_e32 v48, 8, v47
	v_ashrrev_i32_e32 v47, 31, v46
	v_mad_i64_i32 v[48:49], s[0:1], v48, s3, v[28:29]
	v_lshlrev_b64 v[46:47], 11, v[46:47]
	v_lshl_add_u64 v[54:55], v[48:49], 0, s[48:49]
	v_lshl_add_u64 v[58:59], v[24:25], 0, v[46:47]
	v_lshl_add_u64 v[46:47], v[54:55], 0, v[66:67]
	v_lshl_add_u64 v[56:57], v[48:49], 0, v[66:67]
	global_load_dwordx4 v[46:49], v[46:47], off
	s_nop 0
	global_load_dwordx4 v[50:53], v[56:57], off
	v_lshl_add_u64 v[60:61], v[54:55], 0, v[68:69]
	v_add_u32_e32 v64, s18, v64
	v_lshl_add_u64 v[26:27], v[26:27], 0, s[26:27]
	s_waitcnt vmcnt(5)
	v_pk_mul_f32 v[62:63], v[40:41], v[40:41]
	v_pk_mul_f32 v[74:75], v[38:39], v[38:39]
	s_waitcnt vmcnt(4)
	v_pk_mul_f32 v[76:77], v[44:45], v[44:45]
	v_pk_mul_f32 v[78:79], v[42:43], v[42:43]
	v_pk_mov_b32 v[84:85], v[74:75], v[62:63] op_sel:[1,0]
	v_mov_b32_e32 v75, v63
	v_pk_mov_b32 v[62:63], v[78:79], v[76:77] op_sel:[1,0]
	v_mov_b32_e32 v79, v77
	s_waitcnt vmcnt(3)
	v_mul_f32_e32 v83, v17, v17
	s_waitcnt vmcnt(2)
	v_mul_f32_e32 v80, v21, v21
	v_mul_f32_e32 v82, v23, v23
	v_pk_add_f32 v[74:75], v[84:85], v[74:75]
	v_pk_add_f32 v[62:63], v[62:63], v[78:79]
	v_mul_f32_e32 v65, v16, v16
	v_mul_f32_e32 v86, v18, v18
	v_mul_f32_e32 v87, v19, v19
	v_pk_fma_f32 v[76:77], v[20:21], v[20:21], v[80:81] op_sel_hi:[1,1,0]
	v_pk_fma_f32 v[80:81], v[22:23], v[22:23], v[82:83] op_sel_hi:[1,1,0]
	v_pk_add_f32 v[74:75], v[74:75], v[74:75] op_sel:[0,1] op_sel_hi:[1,0]
	v_pk_add_f32 v[62:63], v[62:63], v[62:63] op_sel:[0,1] op_sel_hi:[1,0]
	v_mov_b32_e32 v77, v86
	v_mov_b32_e32 v81, v87
	v_mov_b32_e32 v75, v65
	v_mov_b32_e32 v63, v83
	v_pk_add_f32 v[76:77], v[76:77], v[80:81]
	v_pk_add_f32 v[62:63], v[74:75], v[62:63]
	s_waitcnt vmcnt(1)
	v_pk_add_f32 v[46:47], v[46:47], 1.0 op_sel_hi:[1,0]
	v_pk_add_f32 v[62:63], v[62:63], v[76:77]
	v_pk_add_f32 v[48:49], v[48:49], 1.0 op_sel_hi:[1,0]
	v_add_f32_e32 v62, v62, v63
	s_nop 1
	v_add_f32_dpp v62, v62, v62 quad_perm:[1,0,3,2] row_mask:0xf bank_mask:0xf
	s_nop 1
	v_add_f32_dpp v62, v62, v62 quad_perm:[2,3,0,1] row_mask:0xf bank_mask:0xf
	s_nop 1
	v_add_f32_dpp v62, v62, v62 row_half_mirror row_mask:0xf bank_mask:0xf
	s_nop 1
	v_add_f32_dpp v62, v62, v62 row_ror:8 row_mask:0xf bank_mask:0xf
	v_mov_b32_e32 v63, v62
	s_nop 1
	v_permlane16_swap_b32_e32 v63, v62
	v_add_f32_e32 v62, v62, v63
	v_mov_b32_e32 v63, v62
	s_nop 1
	v_permlane32_swap_b32_e32 v63, v62
	v_add_f32_e32 v62, v62, v63
	v_fmamk_f32 v62, v62, 0x3a800000, v36
	v_mul_f32_e32 v63, 0x4f800000, v62
	v_cmp_gt_f32_e32 vcc, s6, v62
	s_nop 1
	v_cndmask_b32_e32 v62, v62, v63, vcc
	v_sqrt_f32_e32 v63, v62
	s_nop 0
	v_add_u32_e32 v65, -1, v63
	v_add_u32_e32 v74, 1, v63
	v_fma_f32 v75, -v65, v63, v62
	v_fma_f32 v76, -v74, v63, v62
	v_cmp_ge_f32_e64 s[0:1], 0, v75
	s_nop 1
	v_cndmask_b32_e64 v63, v63, v65, s[0:1]
	v_cmp_lt_f32_e64 s[0:1], 0, v76
	s_nop 1
	v_cndmask_b32_e64 v63, v63, v74, s[0:1]
	v_mul_f32_e32 v65, 0x37800000, v63
	v_cndmask_b32_e32 v63, v63, v65, vcc
	v_cmp_class_f32_e32 vcc, v62, v37
	s_nop 1
	v_cndmask_b32_e32 v62, v63, v62, vcc
	v_div_scale_f32 v63, s[0:1], v62, v62, 1.0
	v_rcp_f32_e32 v74, v63
	v_div_scale_f32 v65, vcc, 1.0, v62, 1.0
	v_fma_f32 v75, -v63, v74, 1.0
	v_fmac_f32_e32 v74, v75, v74
	v_mul_f32_e32 v75, v65, v74
	v_fma_f32 v76, -v63, v75, v65
	v_fmac_f32_e32 v75, v76, v74
	v_fma_f32 v63, -v63, v75, v65
	v_div_fmas_f32 v63, v63, v74, v75
	v_div_fixup_f32 v62, v63, v62, 1.0
	v_pk_mul_f32 v[38:39], v[38:39], v[62:63] op_sel_hi:[1,0]
	v_pk_mul_f32 v[40:41], v[40:41], v[62:63] op_sel_hi:[1,0]
	v_pk_mul_f32 v[38:39], v[0:1], v[38:39]
	v_pk_mul_f32 v[40:41], v[2:3], v[40:41]
	s_waitcnt vmcnt(0)
	v_pk_fma_f32 v[38:39], v[46:47], v[38:39], v[50:51]
	v_pk_fma_f32 v[40:41], v[48:49], v[40:41], v[52:53]
	v_cvt_pk_bf16_f32 v38, v38, v39
	v_pk_mul_f32 v[42:43], v[42:43], v[62:63] op_sel_hi:[1,0]
	v_cvt_pk_bf16_f32 v39, v40, v41
	global_store_dwordx2 v[58:59], v[38:39], off
	global_load_dwordx4 v[38:41], v[60:61], off
	s_nop 0
	global_load_dwordx4 v[46:49], v[56:57], off offset:1024
	v_pk_mul_f32 v[44:45], v[44:45], v[62:63] op_sel_hi:[1,0]
	v_pk_mul_f32 v[42:43], v[4:5], v[42:43]
	v_pk_mul_f32 v[44:45], v[6:7], v[44:45]
	v_lshl_add_u64 v[50:51], v[54:55], 0, v[70:71]
	v_pk_mul_f32 v[20:21], v[20:21], v[62:63] op_sel_hi:[1,0]
	v_pk_mul_f32 v[22:23], v[22:23], v[62:63] op_sel_hi:[1,0]
	v_pk_mul_f32 v[20:21], v[8:9], v[20:21]
	v_pk_mul_f32 v[22:23], v[10:11], v[22:23]
	v_pk_mul_f32 v[16:17], v[16:17], v[62:63] op_sel_hi:[1,0]
	v_cmp_lt_i32_e32 vcc, s7, v64
	v_pk_mul_f32 v[18:19], v[18:19], v[62:63] op_sel_hi:[1,0]
	v_pk_mul_f32 v[16:17], v[12:13], v[16:17]
	s_or_b64 s[30:31], vcc, s[30:31]
	v_pk_mul_f32 v[18:19], v[14:15], v[18:19]
	s_waitcnt vmcnt(1)
	v_pk_add_f32 v[38:39], v[38:39], 1.0 op_sel_hi:[1,0]
	v_pk_add_f32 v[40:41], v[40:41], 1.0 op_sel_hi:[1,0]
	s_waitcnt vmcnt(0)
	v_pk_fma_f32 v[38:39], v[38:39], v[42:43], v[46:47]
	v_pk_fma_f32 v[40:41], v[40:41], v[44:45], v[48:49]
	v_cvt_pk_bf16_f32 v38, v38, v39
	v_lshl_add_u64 v[46:47], v[54:55], 0, v[72:73]
	v_cvt_pk_bf16_f32 v39, v40, v41
	global_store_dwordx2 v[58:59], v[38:39], off offset:512
	global_load_dwordx4 v[38:41], v[50:51], off
	s_nop 0
	global_load_dwordx4 v[42:45], v[56:57], off offset:2048
	s_waitcnt vmcnt(1)
	v_pk_add_f32 v[38:39], v[38:39], 1.0 op_sel_hi:[1,0]
	v_pk_add_f32 v[40:41], v[40:41], 1.0 op_sel_hi:[1,0]
	s_waitcnt vmcnt(0)
	v_pk_fma_f32 v[20:21], v[38:39], v[20:21], v[42:43]
	v_pk_fma_f32 v[22:23], v[40:41], v[22:23], v[44:45]
	v_cvt_pk_bf16_f32 v20, v20, v21
	s_nop 0
	v_cvt_pk_bf16_f32 v21, v22, v23
	global_store_dwordx2 v[58:59], v[20:21], off offset:1024
	global_load_dwordx4 v[20:23], v[46:47], off
	s_nop 0
	global_load_dwordx4 v[38:41], v[56:57], off offset:3072
	s_waitcnt vmcnt(1)
	v_pk_add_f32 v[20:21], v[20:21], 1.0 op_sel_hi:[1,0]
	v_pk_add_f32 v[22:23], v[22:23], 1.0 op_sel_hi:[1,0]
	s_waitcnt vmcnt(0)
	v_pk_fma_f32 v[16:17], v[16:17], v[20:21], v[38:39]
	v_pk_fma_f32 v[18:19], v[18:19], v[22:23], v[40:41]
	v_cvt_pk_bf16_f32 v16, v16, v17
	s_nop 0
	v_cvt_pk_bf16_f32 v17, v18, v19
	global_store_dwordx2 v[58:59], v[16:17], off offset:1536
	s_andn2_b64 exec, exec, s[30:31]
	s_cbranch_execnz .LBB0_256

.LBB0_496:
	v_lshlrev_b32_e32 v96, 16, v42
	v_and_b32_e32 v61, 0xffff0000, v42
	v_lshlrev_b32_e32 v98, 16, v43
	v_and_b32_e32 v99, 0xffff0000, v43
	v_lshlrev_b32_e32 v43, 16, v45
	v_lshlrev_b32_e32 v42, 16, v44
	v_and_b32_e32 v45, 0xffff0000, v45
	v_and_b32_e32 v44, 0xffff0000, v44
	v_lshlrev_b32_e32 v103, 16, v47
	v_lshlrev_b32_e32 v102, 16, v46
	v_and_b32_e32 v47, 0xffff0000, v47
	v_and_b32_e32 v46, 0xffff0000, v46
	v_lshlrev_b32_e32 v94, 16, v40
	v_and_b32_e32 v95, 0xffff0000, v40
	v_pk_mul_f32 v[100:101], v[44:45], v[44:45]
	v_pk_mul_f32 v[104:105], v[46:47], v[46:47]
	v_lshlrev_b32_e32 v108, 16, v41
	v_pk_fma_f32 v[100:101], v[42:43], v[42:43], v[100:101]
	v_pk_fma_f32 v[104:105], v[102:103], v[102:103], v[104:105]
	v_mul_f32_e32 v97, v94, v94
	v_mul_f32_e32 v107, v95, v95
	v_and_b32_e32 v109, 0xffff0000, v41
	v_mul_f32_e32 v40, v108, v108
	v_mov_b32_e32 v106, v96
	v_pk_add_f32 v[100:101], v[100:101], v[100:101] op_sel_hi:[0,1]
	v_pk_add_f32 v[104:105], v[104:105], v[104:105] op_sel_hi:[0,1]
	v_pk_fma_f32 v[40:41], v[108:109], v[108:109], v[40:41] op_sel_hi:[1,1,0]
	v_pk_add_f32 v[106:107], v[96:97], v[106:107]
	v_mul_f32_e32 v40, v61, v61
	v_mul_f32_e32 v100, v98, v98
	v_mul_f32_e32 v104, v99, v99
	v_mul_f32_e32 v110, v96, v96
	v_mov_b32_e32 v111, v107
	v_pk_add_f32 v[40:41], v[110:111], v[40:41]
	v_pk_add_f32 v[100:101], v[100:101], v[104:105]
	s_add_u32 s56, s56, 0x800
	v_pk_add_f32 v[40:41], v[40:41], v[100:101]
	s_addc_u32 s57, s57, 0
	v_add_f32_e32 v40, v40, v41
	s_add_u32 s54, s54, 0x400
	s_addc_u32 s55, s55, 0
	s_cmpk_lg_i32 s56, 0x4000
	s_nop 1
	v_add_f32_dpp v40, v40, v40 quad_perm:[1,0,3,2] row_mask:0xf bank_mask:0xf
	s_nop 1
	v_add_f32_dpp v40, v40, v40 quad_perm:[2,3,0,1] row_mask:0xf bank_mask:0xf
	s_nop 1
	v_add_f32_dpp v40, v40, v40 row_half_mirror row_mask:0xf bank_mask:0xf
	s_nop 1
	v_add_f32_dpp v40, v40, v40 row_ror:8 row_mask:0xf bank_mask:0xf
	v_mov_b32_e32 v41, v40
	s_nop 1
	v_permlane16_swap_b32_e32 v41, v40
	v_add_f32_e32 v40, v40, v41
	v_mov_b32_e32 v41, v40
	s_nop 1
	v_permlane32_swap_b32_e32 v41, v40
	v_add_f32_e32 v40, v40, v41
	v_fmamk_f32 v40, v40, 0x3a800000, v49
	v_mul_f32_e32 v41, 0x4f800000, v40
	v_cmp_gt_f32_e32 vcc, s8, v40
	s_nop 1
	v_cndmask_b32_e32 v40, v40, v41, vcc
	v_sqrt_f32_e32 v41, v40
	s_nop 0
	v_add_u32_e32 v97, -1, v41
	v_fma_f32 v100, -v97, v41, v40
	v_cmp_ge_f32_e64 s[0:1], 0, v100
	v_add_u32_e32 v100, 1, v41
	s_nop 0
	v_cndmask_b32_e64 v97, v41, v97, s[0:1]
	v_fma_f32 v41, -v100, v41, v40
	v_cmp_lt_f32_e64 s[0:1], 0, v41
	s_nop 1
	v_cndmask_b32_e64 v41, v97, v100, s[0:1]
	v_mul_f32_e32 v97, 0x37800000, v41
	v_cndmask_b32_e32 v41, v41, v97, vcc
	v_cmp_class_f32_e32 vcc, v40, v92
	s_nop 1
	v_cndmask_b32_e32 v40, v41, v40, vcc
	v_div_scale_f32 v41, s[0:1], v40, v40, 1.0
	v_rcp_f32_e32 v97, v41
	s_nop 0
	v_fma_f32 v100, -v41, v97, 1.0
	v_fmac_f32_e32 v97, v100, v97
	v_div_scale_f32 v100, vcc, 1.0, v40, 1.0
	v_mul_f32_e32 v101, v100, v97
	v_fma_f32 v104, -v41, v101, v100
	v_fmac_f32_e32 v101, v104, v97
	v_fma_f32 v41, -v41, v101, v100
	v_div_fmas_f32 v41, v41, v97, v101
	v_div_fixup_f32 v100, v41, v40, 1.0
	v_mov_b32_e32 v40, v42
	v_mov_b32_e32 v41, v44
	v_mov_b32_e32 v44, v43
	v_pk_mul_f32 v[40:41], v[100:101], v[40:41] op_sel_hi:[0,1]
	v_pk_mul_f32 v[42:43], v[100:101], v[44:45] op_sel_hi:[0,1]
	v_mov_b32_e32 v44, v102
	v_mov_b32_e32 v45, v46
	v_mov_b32_e32 v46, v103
	v_pk_fma_f32 v[42:43], v[70:71], v[42:43], v[22:23]
	v_pk_fma_f32 v[40:41], v[72:73], v[40:41], v[20:21]
	v_pk_mul_f32 v[44:45], v[100:101], v[44:45] op_sel_hi:[0,1]
	v_pk_mul_f32 v[46:47], v[100:101], v[46:47] op_sel_hi:[0,1]
	v_lshl_add_u64 v[104:105], s[6:7], 1, v[68:69]
	v_pk_fma_f32 v[46:47], v[74:75], v[46:47], v[18:19]
	v_pk_fma_f32 v[44:45], v[76:77], v[44:45], v[16:17]
	v_cvt_pk_bf16_f32 v40, v40, v41
	v_cvt_pk_bf16_f32 v41, v42, v43
	v_mov_b32_e32 v97, v61
	v_cvt_pk_bf16_f32 v42, v44, v45
	v_cvt_pk_bf16_f32 v43, v46, v47
	global_store_dwordx4 v[104:105], v[40:43], off
	v_pk_mul_f32 v[44:45], v[96:97], v[100:101] op_sel_hi:[1,0]
	v_pk_mul_f32 v[46:47], v[98:99], v[100:101] op_sel_hi:[1,0]
	v_pk_mul_f32 v[40:41], v[94:95], v[100:101] op_sel_hi:[1,0]
	v_pk_mul_f32 v[42:43], v[108:109], v[100:101] op_sel_hi:[1,0]
	v_pk_fma_f32 v[40:41], v[80:81], v[40:41], v[28:29]
	v_pk_fma_f32 v[42:43], v[78:79], v[42:43], v[30:31]
	v_pk_fma_f32 v[46:47], v[82:83], v[46:47], v[26:27]
	v_pk_fma_f32 v[44:45], v[84:85], v[44:45], v[24:25]
	v_cvt_pk_bf16_f32 v40, v40, v41
	v_cvt_pk_bf16_f32 v41, v42, v43
	s_nop 0
	v_cvt_pk_bf16_f32 v42, v44, v45
	v_cvt_pk_bf16_f32 v43, v46, v47
	global_store_dwordx4 v[104:105], v[40:43], off offset:1024
	s_waitcnt vmcnt(3)
	v_mov_b32_e32 v44, v32
	v_mov_b32_e32 v45, v33
	v_mov_b32_e32 v46, v34
	v_mov_b32_e32 v47, v35
	s_waitcnt vmcnt(2)
	v_mov_b32_e32 v40, v36
	v_mov_b32_e32 v41, v37
	v_mov_b32_e32 v42, v38
	v_mov_b32_e32 v43, v39
	s_cbranch_scc0 .LBB0_494

.LBB0_501:
	v_lshl_add_u64 v[34:35], v[20:21], 0, v[48:49]
	v_add_co_u32_e64 v80, s[0:1], s3, v34
	v_lshl_add_u64 v[36:37], v[24:25], 0, v[48:49]
	s_nop 0
	v_addc_co_u32_e64 v81, s[0:1], 0, v35, s[0:1]
	v_add_co_u32_e64 v96, s[0:1], s6, v34
	v_add_u32_e32 v232, 0x4000, v50
	s_nop 0
	v_addc_co_u32_e64 v97, s[0:1], 0, v35, s[0:1]
	v_add_co_u32_e64 v112, s[0:1], s7, v34
	global_load_dwordx4 v[52:55], v[36:37], off
	global_load_dwordx4 v[56:59], v[36:37], off offset:1024
	global_load_dwordx4 v[60:63], v[36:37], off offset:2048
	global_load_dwordx4 v[64:67], v[36:37], off offset:3072
	v_addc_co_u32_e64 v113, s[0:1], 0, v35, s[0:1]
	v_add_co_u32_e64 v128, s[0:1], s8, v34
	v_add_co_u32_e32 v36, vcc, 0xe600000, v34
	s_nop 0
	v_addc_co_u32_e64 v129, s[0:1], 0, v35, s[0:1]
	v_add_co_u32_e64 v146, s[0:1], s9, v34
	v_ashrrev_i32_e32 v233, 31, v232
	s_nop 0
	v_addc_co_u32_e64 v147, s[0:1], 0, v35, s[0:1]
	v_add_co_u32_e64 v162, s[0:1], s10, v34
	v_addc_co_u32_e32 v37, vcc, 0, v35, vcc
	s_nop 0
	v_addc_co_u32_e64 v163, s[0:1], 0, v35, s[0:1]
	v_add_co_u32_e64 v180, s[0:1], s11, v34
	v_lshlrev_b64 v[250:251], 11, v[232:233]
	s_nop 0
	v_addc_co_u32_e64 v181, s[0:1], 0, v35, s[0:1]
	v_add_co_u32_e64 v196, s[0:1], s12, v34
	v_ashrrev_i32_e32 v51, 2, v50
	s_nop 0
	v_addc_co_u32_e64 v197, s[0:1], 0, v35, s[0:1]
	v_add_co_u32_e64 v212, s[0:1], s13, v34
	v_lshl_add_u64 v[38:39], v[22:23], 0, v[48:49]
	s_nop 0
	v_addc_co_u32_e64 v213, s[0:1], 0, v35, s[0:1]
	v_add_co_u32_e64 v228, s[0:1], s14, v34
	v_add_u32_e32 v51, 8, v51
	s_nop 0
	v_addc_co_u32_e64 v229, s[0:1], 0, v35, s[0:1]
	global_load_dwordx4 v[68:71], v[80:81], off
	global_load_dwordx4 v[72:75], v[80:81], off offset:1024
	global_load_dwordx4 v[76:79], v[80:81], off offset:2048
	s_nop 0
	global_load_dwordx4 v[80:83], v[80:81], off offset:3072
	s_nop 0
	global_load_dwordx4 v[84:87], v[96:97], off
	global_load_dwordx4 v[88:91], v[96:97], off offset:1024
	global_load_dwordx4 v[92:95], v[96:97], off offset:2048
	s_nop 0
	global_load_dwordx4 v[96:99], v[96:97], off offset:3072
	s_nop 0
	global_load_dwordx4 v[100:103], v[112:113], off
	global_load_dwordx4 v[104:107], v[112:113], off offset:1024
	global_load_dwordx4 v[108:111], v[112:113], off offset:2048
	s_nop 0
	global_load_dwordx4 v[112:115], v[112:113], off offset:3072
	s_nop 0
	global_load_dwordx4 v[116:119], v[128:129], off
	global_load_dwordx4 v[120:123], v[128:129], off offset:1024
	global_load_dwordx4 v[124:127], v[128:129], off offset:2048
	s_nop 0
	global_load_dwordx4 v[128:131], v[128:129], off offset:3072
	s_nop 0
	global_load_dwordx4 v[132:135], v[146:147], off
	global_load_dwordx4 v[136:139], v[146:147], off offset:1024
	global_load_dwordx4 v[140:143], v[146:147], off offset:2048
	s_nop 0
	global_load_dwordx4 v[146:149], v[146:147], off offset:3072
	s_nop 0
	global_load_dwordx4 v[150:153], v[162:163], off
	global_load_dwordx4 v[154:157], v[162:163], off offset:1024
	global_load_dwordx4 v[158:161], v[162:163], off offset:2048
	s_nop 0
	global_load_dwordx4 v[162:165], v[162:163], off offset:3072
	s_nop 0
	global_load_dwordx4 v[166:169], v[180:181], off
	global_load_dwordx4 v[170:173], v[180:181], off offset:1024
	global_load_dwordx4 v[176:179], v[180:181], off offset:2048
	s_nop 0
	global_load_dwordx4 v[180:183], v[180:181], off offset:3072
	s_nop 0
	global_load_dwordx4 v[184:187], v[196:197], off
	global_load_dwordx4 v[188:191], v[196:197], off offset:1024
	global_load_dwordx4 v[192:195], v[196:197], off offset:2048
	s_nop 0
	global_load_dwordx4 v[196:199], v[196:197], off offset:3072
	s_nop 0
	global_load_dwordx4 v[200:203], v[212:213], off
	global_load_dwordx4 v[204:207], v[212:213], off offset:1024
	global_load_dwordx4 v[208:211], v[212:213], off offset:2048
	s_nop 0
	global_load_dwordx4 v[212:215], v[212:213], off offset:3072
	s_nop 0
	s_nop 0
	s_nop 0
	global_load_dwordx4 v[232:235], v[36:37], off
	global_load_dwordx4 v[236:239], v[36:37], off offset:1024
	global_load_dwordx4 v[240:243], v[36:37], off offset:2048
	global_load_dwordx4 v[244:247], v[36:37], off offset:3072
	v_add_co_u32_e64 v248, s[0:1], s16, v38
	v_add_u32_e32 v50, s30, v50
	s_nop 0
	v_addc_co_u32_e64 v249, s[0:1], 0, v39, s[0:1]
	v_mad_i64_i32 v[34:35], s[0:1], v51, s15, v[26:27]
	v_lshl_add_u64 v[38:39], v[34:35], 0, s[50:51]
	v_lshl_add_u64 v[36:37], v[34:35], 0, s[52:53]
	v_lshl_add_u64 v[34:35], v[18:19], 0, v[250:251]
	v_lshl_add_u64 v[250:251], v[38:39], 0, v[16:17]
	v_lshl_add_u64 v[252:253], v[36:37], 0, v[16:17]
	v_lshl_add_u64 v[20:21], v[20:21], 0, s[48:49]
	v_lshl_add_u64 v[22:23], v[22:23], 0, s[48:49]
	v_lshl_add_u64 v[24:25], v[24:25], 0, s[48:49]
	s_waitcnt vmcnt(0)
	v_pk_add_f32 v[54:55], v[54:55], v[234:235]
	v_pk_add_f32 v[52:53], v[52:53], v[232:233]
	v_pk_add_f32 v[58:59], v[58:59], v[238:239]
	v_pk_add_f32 v[56:57], v[56:57], v[236:237]
	v_pk_add_f32 v[62:63], v[62:63], v[242:243]
	v_pk_add_f32 v[60:61], v[60:61], v[240:241]
	v_pk_add_f32 v[66:67], v[66:67], v[246:247]
	v_pk_add_f32 v[64:65], v[64:65], v[244:245]
	v_pk_add_f32 v[54:55], v[54:55], v[70:71]
	v_pk_add_f32 v[52:53], v[52:53], v[68:69]
	v_pk_add_f32 v[58:59], v[58:59], v[74:75]
	v_pk_add_f32 v[56:57], v[56:57], v[72:73]
	v_pk_add_f32 v[62:63], v[62:63], v[78:79]
	v_pk_add_f32 v[60:61], v[60:61], v[76:77]
	v_pk_add_f32 v[66:67], v[66:67], v[82:83]
	v_pk_add_f32 v[64:65], v[64:65], v[80:81]
	v_pk_add_f32 v[54:55], v[54:55], v[86:87]
	v_pk_add_f32 v[52:53], v[52:53], v[84:85]
	v_pk_add_f32 v[58:59], v[58:59], v[90:91]
	v_pk_add_f32 v[56:57], v[56:57], v[88:89]
	v_pk_add_f32 v[62:63], v[62:63], v[94:95]
	v_pk_add_f32 v[60:61], v[60:61], v[92:93]
	v_pk_add_f32 v[66:67], v[66:67], v[98:99]
	v_pk_add_f32 v[64:65], v[64:65], v[96:97]
	v_pk_add_f32 v[54:55], v[54:55], v[102:103]
	v_pk_add_f32 v[52:53], v[52:53], v[100:101]
	v_pk_add_f32 v[58:59], v[58:59], v[106:107]
	v_pk_add_f32 v[56:57], v[56:57], v[104:105]
	v_pk_add_f32 v[62:63], v[62:63], v[110:111]
	v_pk_add_f32 v[60:61], v[60:61], v[108:109]
	v_pk_add_f32 v[66:67], v[66:67], v[114:115]
	v_pk_add_f32 v[64:65], v[64:65], v[112:113]
	v_pk_add_f32 v[54:55], v[54:55], v[118:119]
	v_pk_add_f32 v[52:53], v[52:53], v[116:117]
	v_pk_add_f32 v[58:59], v[58:59], v[122:123]
	v_pk_add_f32 v[56:57], v[56:57], v[120:121]
	v_pk_add_f32 v[62:63], v[62:63], v[126:127]
	v_pk_add_f32 v[60:61], v[60:61], v[124:125]
	v_pk_add_f32 v[66:67], v[66:67], v[130:131]
	v_pk_add_f32 v[64:65], v[64:65], v[128:129]
	v_pk_add_f32 v[54:55], v[54:55], v[134:135]
	v_pk_add_f32 v[52:53], v[52:53], v[132:133]
	v_pk_add_f32 v[58:59], v[58:59], v[138:139]
	v_pk_add_f32 v[56:57], v[56:57], v[136:137]
	v_pk_add_f32 v[62:63], v[62:63], v[142:143]
	v_pk_add_f32 v[60:61], v[60:61], v[140:141]
	v_pk_add_f32 v[66:67], v[66:67], v[148:149]
	v_pk_add_f32 v[64:65], v[64:65], v[146:147]
	v_pk_add_f32 v[54:55], v[54:55], v[152:153]
	v_pk_add_f32 v[52:53], v[52:53], v[150:151]
	v_pk_add_f32 v[58:59], v[58:59], v[156:157]
	v_pk_add_f32 v[56:57], v[56:57], v[154:155]
	v_pk_add_f32 v[62:63], v[62:63], v[160:161]
	v_pk_add_f32 v[60:61], v[60:61], v[158:159]
	v_pk_add_f32 v[66:67], v[66:67], v[164:165]
	v_pk_add_f32 v[64:65], v[64:65], v[162:163]
	v_pk_add_f32 v[54:55], v[54:55], v[168:169]
	v_pk_add_f32 v[52:53], v[52:53], v[166:167]
	v_pk_add_f32 v[58:59], v[58:59], v[172:173]
	v_pk_add_f32 v[56:57], v[56:57], v[170:171]
	v_pk_add_f32 v[62:63], v[62:63], v[178:179]
	v_pk_add_f32 v[60:61], v[60:61], v[176:177]
	v_pk_add_f32 v[66:67], v[66:67], v[182:183]
	v_pk_add_f32 v[64:65], v[64:65], v[180:181]
	v_pk_add_f32 v[54:55], v[54:55], v[186:187]
	v_pk_add_f32 v[52:53], v[52:53], v[184:185]
	v_pk_add_f32 v[58:59], v[58:59], v[190:191]
	v_pk_add_f32 v[56:57], v[56:57], v[188:189]
	v_pk_add_f32 v[62:63], v[62:63], v[194:195]
	v_pk_add_f32 v[60:61], v[60:61], v[192:193]
	v_pk_add_f32 v[66:67], v[66:67], v[198:199]
	v_pk_add_f32 v[64:65], v[64:65], v[196:197]
	v_pk_add_f32 v[54:55], v[54:55], v[202:203]
	v_pk_add_f32 v[52:53], v[52:53], v[200:201]
	v_pk_add_f32 v[58:59], v[58:59], v[206:207]
	v_pk_add_f32 v[56:57], v[56:57], v[204:205]
	v_pk_add_f32 v[62:63], v[62:63], v[210:211]
	v_pk_add_f32 v[60:61], v[60:61], v[208:209]
	v_pk_add_f32 v[66:67], v[66:67], v[214:215]
	v_pk_add_f32 v[64:65], v[64:65], v[212:213]
	global_store_dwordx4 v[248:249], v[52:55], off
	global_store_dwordx4 v[248:249], v[56:59], off offset:1024
	global_store_dwordx4 v[248:249], v[60:63], off offset:2048
	global_store_dwordx4 v[248:249], v[64:67], off offset:3072
	v_pk_mul_f32 v[68:69], v[54:55], v[54:55]
	v_pk_mul_f32 v[76:77], v[52:53], v[52:53]
	v_pk_mul_f32 v[70:71], v[58:59], v[58:59]
	v_pk_mul_f32 v[78:79], v[56:57], v[56:57]
	v_mul_f32_e32 v72, v61, v61
	v_mul_f32_e32 v74, v63, v63
	v_pk_mov_b32 v[80:81], v[76:77], v[68:69] op_sel:[1,0]
	v_mov_b32_e32 v77, v69
	v_pk_mov_b32 v[82:83], v[78:79], v[70:71] op_sel:[1,0]
	v_mov_b32_e32 v79, v71
	v_pk_fma_f32 v[84:85], v[60:61], v[60:61], v[72:73] op_sel_hi:[1,1,0]
	v_pk_fma_f32 v[86:87], v[62:63], v[62:63], v[74:75] op_sel_hi:[1,1,0]
	global_load_dwordx4 v[68:71], v[250:251], off
	global_load_dwordx4 v[72:75], v[252:253], off
	v_lshl_add_u64 v[124:125], v[38:39], 0, v[28:29]
	v_lshl_add_u64 v[126:127], v[36:37], 0, v[28:29]
	global_load_dwordx4 v[100:103], v[124:125], off
	global_load_dwordx4 v[104:107], v[126:127], off
	v_lshl_add_u64 v[128:129], v[38:39], 0, v[30:31]
	v_lshl_add_u64 v[130:131], v[36:37], 0, v[30:31]
	global_load_dwordx4 v[108:111], v[128:129], off
	global_load_dwordx4 v[112:115], v[130:131], off
	v_lshl_add_u64 v[132:133], v[38:39], 0, v[32:33]
	v_lshl_add_u64 v[134:135], v[36:37], 0, v[32:33]
	global_load_dwordx4 v[116:119], v[132:133], off
	global_load_dwordx4 v[120:123], v[134:135], off
	v_pk_add_f32 v[76:77], v[80:81], v[76:77]
	v_pk_add_f32 v[78:79], v[82:83], v[78:79]
	v_mul_f32_e32 v51, v64, v64
	v_mul_f32_e32 v88, v65, v65
	v_mul_f32_e32 v89, v66, v66
	v_mul_f32_e32 v90, v67, v67
	v_pk_add_f32 v[76:77], v[76:77], v[76:77] op_sel:[0,1] op_sel_hi:[1,0]
	v_pk_add_f32 v[78:79], v[78:79], v[78:79] op_sel:[0,1] op_sel_hi:[1,0]
	v_mov_b32_e32 v85, v89
	v_mov_b32_e32 v87, v90
	v_mov_b32_e32 v77, v51
	v_mov_b32_e32 v79, v88
	v_pk_add_f32 v[80:81], v[84:85], v[86:87]
	v_pk_add_f32 v[76:77], v[76:77], v[78:79]
	v_lshl_add_u64 v[232:233], v[38:39], 0, v[28:29]
	v_pk_add_f32 v[76:77], v[76:77], v[80:81]
	v_lshl_add_u64 v[234:235], v[36:37], 0, v[28:29]
	v_add_f32_e32 v51, v76, v77
	s_nop 1
	v_add_f32_dpp v51, v51, v51 quad_perm:[1,0,3,2] row_mask:0xf bank_mask:0xf
	s_nop 1
	v_add_f32_dpp v51, v51, v51 quad_perm:[2,3,0,1] row_mask:0xf bank_mask:0xf
	s_nop 1
	v_add_f32_dpp v51, v51, v51 row_half_mirror row_mask:0xf bank_mask:0xf
	s_nop 1
	v_add_f32_dpp v51, v51, v51 row_ror:8 row_mask:0xf bank_mask:0xf
	v_mov_b32_e32 v76, v51
	s_nop 1
	v_permlane16_swap_b32_e32 v76, v51
	v_add_f32_e32 v51, v51, v76
	v_mov_b32_e32 v76, v51
	s_nop 1
	v_permlane32_swap_b32_e32 v76, v51
	v_add_f32_e32 v51, v51, v76
	v_fmamk_f32 v51, v51, 0x3a800000, v46
	v_mul_f32_e32 v76, 0x4f800000, v51
	v_cmp_gt_f32_e32 vcc, s13, v51
	s_waitcnt vmcnt(0)
	v_pk_add_f32 v[68:69], v[68:69], 1.0 op_sel_hi:[1,0]
	v_cndmask_b32_e32 v51, v51, v76, vcc
	v_sqrt_f32_e32 v76, v51
	v_pk_add_f32 v[70:71], v[70:71], 1.0 op_sel_hi:[1,0]
	v_add_u32_e32 v77, -1, v76
	v_add_u32_e32 v78, 1, v76
	v_fma_f32 v79, -v77, v76, v51
	v_fma_f32 v80, -v78, v76, v51
	v_cmp_ge_f32_e64 s[0:1], 0, v79
	s_nop 1
	v_cndmask_b32_e64 v76, v76, v77, s[0:1]
	v_cmp_lt_f32_e64 s[0:1], 0, v80
	s_nop 1
	v_cndmask_b32_e64 v76, v76, v78, s[0:1]
	v_mul_f32_e32 v77, 0x37800000, v76
	v_cndmask_b32_e32 v76, v76, v77, vcc
	v_cmp_class_f32_e32 vcc, v51, v47
	s_nop 1
	v_cndmask_b32_e32 v51, v76, v51, vcc
	v_div_scale_f32 v76, s[0:1], v51, v51, 1.0
	v_rcp_f32_e32 v78, v76
	v_div_scale_f32 v77, vcc, 1.0, v51, 1.0
	v_fma_f32 v79, -v76, v78, 1.0
	v_fmac_f32_e32 v78, v79, v78
	v_mul_f32_e32 v79, v77, v78
	v_fma_f32 v80, -v76, v79, v77
	v_fmac_f32_e32 v79, v80, v78
	v_fma_f32 v76, -v76, v79, v77
	v_div_fmas_f32 v76, v76, v78, v79
	v_div_fixup_f32 v76, v76, v51, 1.0
	v_pk_mul_f32 v[52:53], v[52:53], v[76:77] op_sel_hi:[1,0]
	v_pk_mul_f32 v[54:55], v[54:55], v[76:77] op_sel_hi:[1,0]
	v_pk_mul_f32 v[52:53], v[0:1], v[52:53]
	v_pk_mul_f32 v[54:55], v[2:3], v[54:55]
	s_waitcnt vmcnt(0)
	v_pk_fma_f32 v[52:53], v[68:69], v[52:53], v[72:73]
	v_pk_fma_f32 v[54:55], v[70:71], v[54:55], v[74:75]
	v_cvt_pk_bf16_f32 v52, v52, v53
	v_pk_mul_f32 v[56:57], v[56:57], v[76:77] op_sel_hi:[1,0]
	v_cvt_pk_bf16_f32 v53, v54, v55
	global_store_dwordx2 v[34:35], v[52:53], off
	s_nop 1
	s_nop 0
	v_pk_mul_f32 v[58:59], v[58:59], v[76:77] op_sel_hi:[1,0]
	v_pk_mul_f32 v[56:57], v[4:5], v[56:57]
	v_pk_mul_f32 v[58:59], v[6:7], v[58:59]
	v_lshl_add_u64 v[72:73], v[38:39], 0, v[30:31]
	v_lshl_add_u64 v[74:75], v[36:37], 0, v[30:31]
	v_pk_mul_f32 v[60:61], v[60:61], v[76:77] op_sel_hi:[1,0]
	v_lshl_add_u64 v[38:39], v[38:39], 0, v[32:33]
	v_pk_mul_f32 v[60:61], v[8:9], v[60:61]
	v_cmp_lt_i32_e32 vcc, s17, v50
	s_or_b64 s[38:39], vcc, s[38:39]
	v_pk_add_f32 v[52:53], v[100:101], 1.0 op_sel_hi:[1,0]
	v_pk_add_f32 v[54:55], v[102:103], 1.0 op_sel_hi:[1,0]
	v_pk_fma_f32 v[52:53], v[52:53], v[56:57], v[104:105]
	v_pk_fma_f32 v[54:55], v[54:55], v[58:59], v[106:107]
	v_cvt_pk_bf16_f32 v52, v52, v53
	v_lshl_add_u64 v[68:69], v[36:37], 0, v[32:33]
	v_cvt_pk_bf16_f32 v53, v54, v55
	global_store_dwordx2 v[34:35], v[52:53], off offset:512
	s_nop 1
	s_nop 0
	v_pk_mul_f32 v[36:37], v[62:63], v[76:77] op_sel_hi:[1,0]
	v_pk_add_f32 v[52:53], v[108:109], 1.0 op_sel_hi:[1,0]
	v_pk_mul_f32 v[36:37], v[10:11], v[36:37]
	v_pk_add_f32 v[54:55], v[110:111], 1.0 op_sel_hi:[1,0]
	v_pk_fma_f32 v[52:53], v[60:61], v[52:53], v[112:113]
	v_pk_fma_f32 v[36:37], v[36:37], v[54:55], v[114:115]
	v_cvt_pk_bf16_f32 v52, v52, v53
	v_pk_mul_f32 v[58:59], v[64:65], v[76:77] op_sel_hi:[1,0]
	v_cvt_pk_bf16_f32 v53, v36, v37
	global_store_dwordx2 v[34:35], v[52:53], off offset:1024
	s_nop 1
	s_nop 0
	v_pk_mul_f32 v[56:57], v[66:67], v[76:77] op_sel_hi:[1,0]
	v_pk_mul_f32 v[58:59], v[12:13], v[58:59]
	v_pk_mul_f32 v[56:57], v[14:15], v[56:57]
	v_pk_add_f32 v[36:37], v[116:117], 1.0 op_sel_hi:[1,0]
	v_pk_add_f32 v[38:39], v[118:119], 1.0 op_sel_hi:[1,0]
	v_pk_fma_f32 v[36:37], v[58:59], v[36:37], v[120:121]
	v_pk_fma_f32 v[38:39], v[56:57], v[38:39], v[122:123]
	v_cvt_pk_bf16_f32 v36, v36, v37
	s_nop 0
	v_cvt_pk_bf16_f32 v37, v38, v39
	global_store_dwordx2 v[34:35], v[36:37], off offset:1536
	s_andn2_b64 exec, exec, s[38:39]
	s_cbranch_execnz .LBB0_501

.LBB0_745:
	v_add_u32_e32 v32, s29, v120
	s_waitcnt lgkmcnt(0)
	s_barrier
	ds_read_b128 v[36:39], v32 offset:63488
	ds_read_b128 v[32:35], v32 offset:63504
	s_lshl_b32 s1, s1, 11
	s_or_b32 s8, s1, s0
	s_add_i32 s7, s7, 32
	s_waitcnt lgkmcnt(1)
	v_mov_b32_e32 v40, v37
	v_mov_b32_e32 v41, v38
	v_mov_b32_e32 v116, v36
	v_mov_b32_e32 v117, v39
	v_pk_add_f32 v[40:41], v[40:41], v[116:117]
	s_waitcnt lgkmcnt(0)
	v_mov_b32_e32 v116, v34
	v_mov_b32_e32 v117, v32
	v_mov_b32_e32 v134, v35
	v_mov_b32_e32 v135, v33
	v_pk_add_f32 v[116:117], v[116:117], v[134:135]
	v_add_f32_e32 v40, v40, v41
	v_add_f32_e32 v40, v40, v117
	v_add_f32_e32 v40, v116, v40
	s_mov_b32 s73, s72
	s_nop 1
	v_add_f32_dpp v40, v40, v40 quad_perm:[1,0,3,2] row_mask:0xf bank_mask:0xf
	s_nop 1
	v_add_f32_dpp v40, v40, v40 quad_perm:[2,3,0,1] row_mask:0xf bank_mask:0xf
	s_nop 1
	v_add_f32_dpp v40, v40, v40 row_half_mirror row_mask:0xf bank_mask:0xf
	s_nop 1
	v_add_f32_dpp v40, v40, v40 row_ror:8 row_mask:0xf bank_mask:0xf
	v_mov_b32_e32 v41, v40
	s_nop 1
	v_permlane16_swap_b32_e32 v41, v40
	v_add_f32_e32 v40, v40, v41
	v_mov_b32_e32 v41, v40
	s_nop 1
	v_permlane32_swap_b32_e32 v41, v40
	v_add_f32_e32 v40, v40, v41
	v_fmamk_f32 v117, v40, 0xbb000000, v39
	v_fmac_f32_e32 v37, 0xbb000000, v40
	v_fmamk_f32 v116, v40, 0xbb000000, v38
	v_fmamk_f32 v36, v40, 0xbb000000, v36
	v_mul_f32_e32 v38, v37, v37
	v_mul_f32_e32 v39, v117, v117
	v_fmamk_f32 v33, v40, 0xbb000000, v33
	v_fmamk_f32 v32, v40, 0xbb000000, v32
	v_fmamk_f32 v35, v40, 0xbb000000, v35
	v_fmac_f32_e32 v34, 0xbb000000, v40
	v_fmac_f32_e32 v38, v36, v36
	v_fmac_f32_e32 v39, v116, v116
	v_add_f32_e32 v118, v38, v39
	v_pk_mul_f32 v[38:39], v[34:35], v[34:35]
	v_pk_mul_f32 v[40:41], v[32:33], v[32:33]
	v_mov_b32_e32 v134, v38
	v_mov_b32_e32 v135, v40
	v_mov_b32_e32 v40, v39
	v_pk_add_f32 v[38:39], v[134:135], v[40:41]
	s_nop 0
	v_add_f32_e32 v39, v39, v118
	v_add_f32_e32 v38, v38, v39
	s_nop 1
	v_add_f32_dpp v38, v38, v38 quad_perm:[1,0,3,2] row_mask:0xf bank_mask:0xf
	s_nop 1
	v_add_f32_dpp v38, v38, v38 quad_perm:[2,3,0,1] row_mask:0xf bank_mask:0xf
	s_nop 1
	v_add_f32_dpp v38, v38, v38 row_half_mirror row_mask:0xf bank_mask:0xf
	s_nop 1
	v_add_f32_dpp v38, v38, v38 row_ror:8 row_mask:0xf bank_mask:0xf
	v_mov_b32_e32 v39, v38
	s_nop 1
	v_permlane16_swap_b32_e32 v39, v38
	v_add_f32_e32 v38, v38, v39
	v_mov_b32_e32 v39, v38
	s_nop 1
	v_permlane32_swap_b32_e32 v39, v38
	v_add_f32_e32 v38, v38, v39
	v_fmamk_f32 v38, v38, 0x3b000000, v131
	v_cmp_gt_f32_e32 vcc, s71, v38
	v_mul_f32_e32 v39, 0x4f800000, v38
	s_nop 0
	v_cndmask_b32_e32 v38, v38, v39, vcc
	v_sqrt_f32_e32 v39, v38
	s_nop 0
	v_add_u32_e32 v40, -1, v39
	v_fma_f32 v41, -v40, v39, v38
	v_cmp_ge_f32_e64 s[0:1], 0, v41
	v_add_u32_e32 v41, 1, v39
	s_nop 0
	v_cndmask_b32_e64 v40, v39, v40, s[0:1]
	v_fma_f32 v39, -v41, v39, v38
	v_cmp_lt_f32_e64 s[0:1], 0, v39
	s_nop 1
	v_cndmask_b32_e64 v39, v40, v41, s[0:1]
	v_mul_f32_e32 v40, 0x37800000, v39
	v_cndmask_b32_e32 v39, v39, v40, vcc
	v_cmp_class_f32_e32 vcc, v38, v132
	s_nop 1
	v_cndmask_b32_e32 v38, v39, v38, vcc
	v_div_scale_f32 v39, s[0:1], v38, v38, 1.0
	v_rcp_f32_e32 v40, v39
	s_add_i32 s0, s8, s6
	s_ashr_i32 s1, s0, 31
	s_lshl_b64 s[0:1], s[0:1], 11
	v_fma_f32 v41, -v39, v40, 1.0
	v_fmac_f32_e32 v40, v41, v40
	v_div_scale_f32 v41, vcc, 1.0, v38, 1.0
	v_mul_f32_e32 v118, v41, v40
	v_fma_f32 v133, -v39, v118, v41
	v_fmac_f32_e32 v118, v133, v40
	v_fma_f32 v39, -v39, v118, v41
	v_div_fmas_f32 v39, v39, v40, v118
	v_div_fixup_f32 v118, v39, v38, 1.0
	s_nop 0
	s_nop 0
	s_nop 0
	s_nop 0
	v_pk_mul_f32 v[36:37], v[36:37], v[118:119] op_sel_hi:[1,0]
	v_pk_mul_f32 v[32:33], v[32:33], v[118:119] op_sel_hi:[1,0]
	v_pk_mul_f32 v[34:35], v[34:35], v[118:119] op_sel_hi:[1,0]
	v_pk_mul_f32 v[116:117], v[116:117], v[118:119] op_sel_hi:[1,0]
	s_waitcnt vmcnt(0)
	v_pk_fma_f32 v[40:41], v[230:231], v[34:35], v[238:239]
	s_nop 0
	v_pk_fma_f32 v[36:37], v[232:233], v[36:37], v[240:241]
	v_pk_fma_f32 v[34:35], v[228:229], v[32:33], v[236:237]
	v_mul_f32_e32 v32, 0xbfb8aa3b, v36
	v_mul_f32_e32 v33, 0xbfb8aa3b, v37
	v_exp_f32_e32 v32, v32
	v_exp_f32_e32 v33, v33
	v_pk_fma_f32 v[116:117], v[234:235], v[116:117], v[242:243]
	v_add_f32_e32 v32, 1.0, v32
	v_add_f32_e32 v33, 1.0, v33
	v_rcp_f32_e32 v32, v32
	v_rcp_f32_e32 v33, v33
	v_mul_f32_e32 v32, v36, v32
	v_mul_f32_e32 v33, v37, v33
	v_cvt_pk_bf16_f32 v32, v32, v33
	v_mul_f32_e32 v33, 0xbfb8aa3b, v116
	v_mul_f32_e32 v36, 0xbfb8aa3b, v117
	v_exp_f32_e32 v33, v33
	v_exp_f32_e32 v36, v36
	v_add_f32_e32 v33, 1.0, v33
	v_add_f32_e32 v36, 1.0, v36
	v_rcp_f32_e32 v33, v33
	v_rcp_f32_e32 v36, v36
	v_mul_f32_e32 v33, v116, v33
	v_mul_f32_e32 v36, v117, v36
	v_cvt_pk_bf16_f32 v33, v33, v36
	v_mul_f32_e32 v36, 0xbfb8aa3b, v34
	v_exp_f32_e32 v36, v36
	s_nop 0
	v_add_f32_e32 v36, 1.0, v36
	v_rcp_f32_e32 v36, v36
	s_nop 0
	v_mul_f32_e32 v34, v34, v36
	v_mul_f32_e32 v36, 0xbfb8aa3b, v35
	v_exp_f32_e32 v36, v36
	s_nop 0
	v_add_f32_e32 v36, 1.0, v36
	v_rcp_f32_e32 v36, v36
	s_nop 0
	v_mul_f32_e32 v35, v35, v36
	v_cvt_pk_bf16_f32 v34, v34, v35
	v_mul_f32_e32 v35, 0xbfb8aa3b, v40
	v_mul_f32_e32 v36, 0xbfb8aa3b, v41
	v_exp_f32_e32 v35, v35
	v_exp_f32_e32 v36, v36
	v_add_f32_e32 v35, 1.0, v35
	v_add_f32_e32 v36, 1.0, v36
	v_rcp_f32_e32 v35, v35
	v_rcp_f32_e32 v36, v36
	v_mul_f32_e32 v35, v40, v35
	v_mul_f32_e32 v36, v41, v36
	v_cvt_pk_bf16_f32 v35, v35, v36
	v_lshl_add_u64 v[36:37], v[114:115], 0, s[0:1]
	global_store_dwordx4 v[36:37], v[32:35], off offset:1024
	s_nop 1
	v_add_u32_e32 v32, s68, v120
	ds_read_b128 v[36:39], v32 offset:63488
	ds_read_b128 v[32:35], v32 offset:63504
	s_waitcnt lgkmcnt(1)
	v_mov_b32_e32 v40, v37
	v_mov_b32_e32 v41, v38
	v_mov_b32_e32 v116, v36
	v_mov_b32_e32 v117, v39
	v_pk_add_f32 v[40:41], v[40:41], v[116:117]
	s_waitcnt lgkmcnt(0)
	v_mov_b32_e32 v116, v34
	v_mov_b32_e32 v117, v32
	v_mov_b32_e32 v134, v35
	v_mov_b32_e32 v135, v33
	v_pk_add_f32 v[116:117], v[116:117], v[134:135]
	v_add_f32_e32 v40, v40, v41
	v_add_f32_e32 v40, v40, v117
	v_add_f32_e32 v40, v116, v40
	s_nop 1
	v_add_f32_dpp v40, v40, v40 quad_perm:[1,0,3,2] row_mask:0xf bank_mask:0xf
	s_nop 1
	v_add_f32_dpp v40, v40, v40 quad_perm:[2,3,0,1] row_mask:0xf bank_mask:0xf
	s_nop 1
	v_add_f32_dpp v40, v40, v40 row_half_mirror row_mask:0xf bank_mask:0xf
	s_nop 1
	v_add_f32_dpp v40, v40, v40 row_ror:8 row_mask:0xf bank_mask:0xf
	v_mov_b32_e32 v41, v40
	s_nop 1
	v_permlane16_swap_b32_e32 v41, v40
	v_add_f32_e32 v40, v40, v41
	v_mov_b32_e32 v41, v40
	s_nop 1
	v_permlane32_swap_b32_e32 v41, v40
	v_add_f32_e32 v40, v40, v41
	v_fmamk_f32 v117, v40, 0xbb000000, v39
	v_fmac_f32_e32 v37, 0xbb000000, v40
	v_fmamk_f32 v116, v40, 0xbb000000, v38
	v_fmamk_f32 v36, v40, 0xbb000000, v36
	v_mul_f32_e32 v38, v37, v37
	v_mul_f32_e32 v39, v117, v117
	v_fmamk_f32 v33, v40, 0xbb000000, v33
	v_fmamk_f32 v32, v40, 0xbb000000, v32
	v_fmamk_f32 v35, v40, 0xbb000000, v35
	v_fmac_f32_e32 v34, 0xbb000000, v40
	v_fmac_f32_e32 v38, v36, v36
	v_fmac_f32_e32 v39, v116, v116
	v_add_f32_e32 v118, v38, v39
	v_pk_mul_f32 v[38:39], v[34:35], v[34:35]
	v_pk_mul_f32 v[40:41], v[32:33], v[32:33]
	v_mov_b32_e32 v134, v38
	v_mov_b32_e32 v135, v40
	v_mov_b32_e32 v40, v39
	v_pk_add_f32 v[38:39], v[134:135], v[40:41]
	s_nop 0
	v_add_f32_e32 v39, v39, v118
	v_add_f32_e32 v38, v38, v39
	s_nop 1
	v_add_f32_dpp v38, v38, v38 quad_perm:[1,0,3,2] row_mask:0xf bank_mask:0xf
	s_nop 1
	v_add_f32_dpp v38, v38, v38 quad_perm:[2,3,0,1] row_mask:0xf bank_mask:0xf
	s_nop 1
	v_add_f32_dpp v38, v38, v38 row_half_mirror row_mask:0xf bank_mask:0xf
	s_nop 1
	v_add_f32_dpp v38, v38, v38 row_ror:8 row_mask:0xf bank_mask:0xf
	v_mov_b32_e32 v39, v38
	s_nop 1
	v_permlane16_swap_b32_e32 v39, v38
	v_add_f32_e32 v38, v38, v39
	v_mov_b32_e32 v39, v38
	s_nop 1
	v_permlane32_swap_b32_e32 v39, v38
	v_add_f32_e32 v38, v38, v39
	v_fmamk_f32 v38, v38, 0x3b000000, v131
	v_cmp_gt_f32_e32 vcc, s71, v38
	v_mul_f32_e32 v39, 0x4f800000, v38
	s_nop 0
	v_cndmask_b32_e32 v38, v38, v39, vcc
	v_sqrt_f32_e32 v39, v38
	s_nop 0
	v_add_u32_e32 v40, -1, v39
	v_fma_f32 v41, -v40, v39, v38
	v_cmp_ge_f32_e64 s[0:1], 0, v41
	v_add_u32_e32 v41, 1, v39
	s_nop 0
	v_cndmask_b32_e64 v40, v39, v40, s[0:1]
	v_fma_f32 v39, -v41, v39, v38
	v_cmp_lt_f32_e64 s[0:1], 0, v39
	s_nop 1
	v_cndmask_b32_e64 v39, v40, v41, s[0:1]
	v_mul_f32_e32 v40, 0x37800000, v39
	v_cndmask_b32_e32 v39, v39, v40, vcc
	v_cmp_class_f32_e32 vcc, v38, v132
	s_nop 1
	v_cndmask_b32_e32 v38, v39, v38, vcc
	v_div_scale_f32 v39, s[0:1], v38, v38, 1.0
	v_rcp_f32_e32 v40, v39
	s_add_i32 s0, s8, s14
	s_ashr_i32 s1, s0, 31
	s_lshl_b64 s[0:1], s[0:1], 11
	v_fma_f32 v41, -v39, v40, 1.0
	v_fmac_f32_e32 v40, v41, v40
	v_div_scale_f32 v41, vcc, 1.0, v38, 1.0
	v_mul_f32_e32 v118, v41, v40
	v_fma_f32 v133, -v39, v118, v41
	v_fmac_f32_e32 v118, v133, v40
	v_fma_f32 v39, -v39, v118, v41
	v_div_fmas_f32 v39, v39, v40, v118
	v_div_fixup_f32 v118, v39, v38, 1.0
	s_nop 0
	s_nop 0
	s_nop 0
	s_nop 0
	v_pk_mul_f32 v[36:37], v[36:37], v[118:119] op_sel_hi:[1,0]
	v_pk_mul_f32 v[32:33], v[32:33], v[118:119] op_sel_hi:[1,0]
	v_pk_mul_f32 v[34:35], v[34:35], v[118:119] op_sel_hi:[1,0]
	v_pk_mul_f32 v[116:117], v[116:117], v[118:119] op_sel_hi:[1,0]
	s_nop 0
	v_pk_fma_f32 v[40:41], v[230:231], v[34:35], v[238:239]
	s_nop 0
	v_pk_fma_f32 v[36:37], v[232:233], v[36:37], v[240:241]
	v_pk_fma_f32 v[34:35], v[228:229], v[32:33], v[236:237]
	v_mul_f32_e32 v32, 0xbfb8aa3b, v36
	v_mul_f32_e32 v33, 0xbfb8aa3b, v37
	v_exp_f32_e32 v32, v32
	v_exp_f32_e32 v33, v33
	v_pk_fma_f32 v[116:117], v[234:235], v[116:117], v[242:243]
	v_add_f32_e32 v32, 1.0, v32
	v_add_f32_e32 v33, 1.0, v33
	v_rcp_f32_e32 v32, v32
	v_rcp_f32_e32 v33, v33
	v_mul_f32_e32 v32, v36, v32
	v_mul_f32_e32 v33, v37, v33
	v_cvt_pk_bf16_f32 v32, v32, v33
	v_mul_f32_e32 v33, 0xbfb8aa3b, v116
	v_mul_f32_e32 v36, 0xbfb8aa3b, v117
	v_exp_f32_e32 v33, v33
	v_exp_f32_e32 v36, v36
	v_add_f32_e32 v33, 1.0, v33
	v_add_f32_e32 v36, 1.0, v36
	v_rcp_f32_e32 v33, v33
	v_rcp_f32_e32 v36, v36
	v_mul_f32_e32 v33, v116, v33
	v_mul_f32_e32 v36, v117, v36
	v_cvt_pk_bf16_f32 v33, v33, v36
	v_mul_f32_e32 v36, 0xbfb8aa3b, v34
	v_exp_f32_e32 v36, v36
	s_nop 0
	v_add_f32_e32 v36, 1.0, v36
	v_rcp_f32_e32 v36, v36
	s_nop 0
	v_mul_f32_e32 v34, v34, v36
	v_mul_f32_e32 v36, 0xbfb8aa3b, v35
	v_exp_f32_e32 v36, v36
	s_nop 0
	v_add_f32_e32 v36, 1.0, v36
	v_rcp_f32_e32 v36, v36
	s_nop 0
	v_mul_f32_e32 v35, v35, v36
	v_cvt_pk_bf16_f32 v34, v34, v35
	v_mul_f32_e32 v35, 0xbfb8aa3b, v40
	v_mul_f32_e32 v36, 0xbfb8aa3b, v41
	v_exp_f32_e32 v35, v35
	v_exp_f32_e32 v36, v36
	v_add_f32_e32 v35, 1.0, v35
	v_add_f32_e32 v36, 1.0, v36
	v_rcp_f32_e32 v35, v35
	v_rcp_f32_e32 v36, v36
	v_mul_f32_e32 v35, v40, v35
	v_mul_f32_e32 v36, v41, v36
	v_cvt_pk_bf16_f32 v35, v35, v36
	v_lshl_add_u64 v[36:37], v[114:115], 0, s[0:1]
	global_store_dwordx4 v[36:37], v[32:35], off offset:1024
	s_nop 1
	v_add_u32_e32 v32, s69, v120
	ds_read_b128 v[36:39], v32 offset:63488
	ds_read_b128 v[32:35], v32 offset:63504
	s_waitcnt lgkmcnt(1)
	v_mov_b32_e32 v40, v37
	v_mov_b32_e32 v41, v38
	v_mov_b32_e32 v116, v36
	v_mov_b32_e32 v117, v39
	v_pk_add_f32 v[40:41], v[40:41], v[116:117]
	s_waitcnt lgkmcnt(0)
	v_mov_b32_e32 v116, v34
	v_mov_b32_e32 v117, v32
	v_mov_b32_e32 v134, v35
	v_mov_b32_e32 v135, v33
	v_pk_add_f32 v[116:117], v[116:117], v[134:135]
	v_add_f32_e32 v40, v40, v41
	v_add_f32_e32 v40, v40, v117
	v_add_f32_e32 v40, v116, v40
	s_nop 1
	v_add_f32_dpp v40, v40, v40 quad_perm:[1,0,3,2] row_mask:0xf bank_mask:0xf
	s_nop 1
	v_add_f32_dpp v40, v40, v40 quad_perm:[2,3,0,1] row_mask:0xf bank_mask:0xf
	s_nop 1
	v_add_f32_dpp v40, v40, v40 row_half_mirror row_mask:0xf bank_mask:0xf
	s_nop 1
	v_add_f32_dpp v40, v40, v40 row_ror:8 row_mask:0xf bank_mask:0xf
	v_mov_b32_e32 v41, v40
	s_nop 1
	v_permlane16_swap_b32_e32 v41, v40
	v_add_f32_e32 v40, v40, v41
	v_mov_b32_e32 v41, v40
	s_nop 1
	v_permlane32_swap_b32_e32 v41, v40
	v_add_f32_e32 v40, v40, v41
	v_fmamk_f32 v117, v40, 0xbb000000, v39
	v_fmac_f32_e32 v37, 0xbb000000, v40
	v_fmamk_f32 v116, v40, 0xbb000000, v38
	v_fmamk_f32 v36, v40, 0xbb000000, v36
	v_mul_f32_e32 v38, v37, v37
	v_mul_f32_e32 v39, v117, v117
	v_fmamk_f32 v33, v40, 0xbb000000, v33
	v_fmamk_f32 v32, v40, 0xbb000000, v32
	v_fmamk_f32 v35, v40, 0xbb000000, v35
	v_fmac_f32_e32 v34, 0xbb000000, v40
	v_fmac_f32_e32 v38, v36, v36
	v_fmac_f32_e32 v39, v116, v116
	v_add_f32_e32 v118, v38, v39
	v_pk_mul_f32 v[38:39], v[34:35], v[34:35]
	v_pk_mul_f32 v[40:41], v[32:33], v[32:33]
	v_mov_b32_e32 v134, v38
	v_mov_b32_e32 v135, v40
	v_mov_b32_e32 v40, v39
	v_pk_add_f32 v[38:39], v[134:135], v[40:41]
	s_nop 0
	v_add_f32_e32 v39, v39, v118
	v_add_f32_e32 v38, v38, v39
	s_nop 1
	v_add_f32_dpp v38, v38, v38 quad_perm:[1,0,3,2] row_mask:0xf bank_mask:0xf
	s_nop 1
	v_add_f32_dpp v38, v38, v38 quad_perm:[2,3,0,1] row_mask:0xf bank_mask:0xf
	s_nop 1
	v_add_f32_dpp v38, v38, v38 row_half_mirror row_mask:0xf bank_mask:0xf
	s_nop 1
	v_add_f32_dpp v38, v38, v38 row_ror:8 row_mask:0xf bank_mask:0xf
	v_mov_b32_e32 v39, v38
	s_nop 1
	v_permlane16_swap_b32_e32 v39, v38
	v_add_f32_e32 v38, v38, v39
	v_mov_b32_e32 v39, v38
	s_nop 1
	v_permlane32_swap_b32_e32 v39, v38
	v_add_f32_e32 v38, v38, v39
	v_fmamk_f32 v38, v38, 0x3b000000, v131
	v_cmp_gt_f32_e32 vcc, s71, v38
	v_mul_f32_e32 v39, 0x4f800000, v38
	s_nop 0
	v_cndmask_b32_e32 v38, v38, v39, vcc
	v_sqrt_f32_e32 v39, v38
	s_nop 0
	v_add_u32_e32 v40, -1, v39
	v_fma_f32 v41, -v40, v39, v38
	v_cmp_ge_f32_e64 s[0:1], 0, v41
	v_add_u32_e32 v41, 1, v39
	s_nop 0
	v_cndmask_b32_e64 v40, v39, v40, s[0:1]
	v_fma_f32 v39, -v41, v39, v38
	v_cmp_lt_f32_e64 s[0:1], 0, v39
	s_nop 1
	v_cndmask_b32_e64 v39, v40, v41, s[0:1]
	v_mul_f32_e32 v40, 0x37800000, v39
	v_cndmask_b32_e32 v39, v39, v40, vcc
	v_cmp_class_f32_e32 vcc, v38, v132
	s_nop 1
	v_cndmask_b32_e32 v38, v39, v38, vcc
	v_div_scale_f32 v39, s[0:1], v38, v38, 1.0
	v_rcp_f32_e32 v40, v39
	s_add_i32 s0, s8, s15
	s_ashr_i32 s1, s0, 31
	s_lshl_b64 s[0:1], s[0:1], 11
	v_fma_f32 v41, -v39, v40, 1.0
	v_fmac_f32_e32 v40, v41, v40
	v_div_scale_f32 v41, vcc, 1.0, v38, 1.0
	v_mul_f32_e32 v118, v41, v40
	v_fma_f32 v133, -v39, v118, v41
	v_fmac_f32_e32 v118, v133, v40
	v_fma_f32 v39, -v39, v118, v41
	v_div_fmas_f32 v39, v39, v40, v118
	v_div_fixup_f32 v118, v39, v38, 1.0
	s_nop 0
	s_nop 0
	s_nop 0
	s_nop 0
	v_pk_mul_f32 v[36:37], v[36:37], v[118:119] op_sel_hi:[1,0]
	v_pk_mul_f32 v[32:33], v[32:33], v[118:119] op_sel_hi:[1,0]
	v_pk_mul_f32 v[34:35], v[34:35], v[118:119] op_sel_hi:[1,0]
	v_pk_mul_f32 v[116:117], v[116:117], v[118:119] op_sel_hi:[1,0]
	s_nop 0
	v_pk_fma_f32 v[40:41], v[230:231], v[34:35], v[238:239]
	s_nop 0
	v_pk_fma_f32 v[36:37], v[232:233], v[36:37], v[240:241]
	v_pk_fma_f32 v[34:35], v[228:229], v[32:33], v[236:237]
	v_mul_f32_e32 v32, 0xbfb8aa3b, v36
	v_mul_f32_e32 v33, 0xbfb8aa3b, v37
	v_exp_f32_e32 v32, v32
	v_exp_f32_e32 v33, v33
	v_pk_fma_f32 v[116:117], v[234:235], v[116:117], v[242:243]
	v_add_f32_e32 v32, 1.0, v32
	v_add_f32_e32 v33, 1.0, v33
	v_rcp_f32_e32 v32, v32
	v_rcp_f32_e32 v33, v33
	v_mul_f32_e32 v32, v36, v32
	v_mul_f32_e32 v33, v37, v33
	v_cvt_pk_bf16_f32 v32, v32, v33
	v_mul_f32_e32 v33, 0xbfb8aa3b, v116
	v_mul_f32_e32 v36, 0xbfb8aa3b, v117
	v_exp_f32_e32 v33, v33
	v_exp_f32_e32 v36, v36
	v_add_f32_e32 v33, 1.0, v33
	v_add_f32_e32 v36, 1.0, v36
	v_rcp_f32_e32 v33, v33
	v_rcp_f32_e32 v36, v36
	v_mul_f32_e32 v33, v116, v33
	v_mul_f32_e32 v36, v117, v36
	v_cvt_pk_bf16_f32 v33, v33, v36
	v_mul_f32_e32 v36, 0xbfb8aa3b, v34
	v_exp_f32_e32 v36, v36
	s_nop 0
	v_add_f32_e32 v36, 1.0, v36
	v_rcp_f32_e32 v36, v36
	s_nop 0
	v_mul_f32_e32 v34, v34, v36
	v_mul_f32_e32 v36, 0xbfb8aa3b, v35
	v_exp_f32_e32 v36, v36
	s_nop 0
	v_add_f32_e32 v36, 1.0, v36
	v_rcp_f32_e32 v36, v36
	s_nop 0
	v_mul_f32_e32 v35, v35, v36
	v_cvt_pk_bf16_f32 v34, v34, v35
	v_mul_f32_e32 v35, 0xbfb8aa3b, v40
	v_mul_f32_e32 v36, 0xbfb8aa3b, v41
	v_exp_f32_e32 v35, v35
	v_exp_f32_e32 v36, v36
	v_add_f32_e32 v35, 1.0, v35
	v_add_f32_e32 v36, 1.0, v36
	v_rcp_f32_e32 v35, v35
	v_rcp_f32_e32 v36, v36
	v_mul_f32_e32 v35, v40, v35
	v_mul_f32_e32 v36, v41, v36
	v_cvt_pk_bf16_f32 v35, v35, v36
	v_lshl_add_u64 v[36:37], v[114:115], 0, s[0:1]
	global_store_dwordx4 v[36:37], v[32:35], off offset:1024
	s_nop 1
	v_add_u32_e32 v32, s70, v120
	ds_read_b128 v[36:39], v32 offset:63488
	ds_read_b128 v[32:35], v32 offset:63504
	s_waitcnt lgkmcnt(1)
	v_mov_b32_e32 v40, v37
	v_mov_b32_e32 v41, v38
	v_mov_b32_e32 v116, v36
	v_mov_b32_e32 v117, v39
	v_pk_add_f32 v[40:41], v[40:41], v[116:117]
	s_waitcnt lgkmcnt(0)
	v_mov_b32_e32 v116, v34
	v_mov_b32_e32 v117, v32
	v_mov_b32_e32 v134, v35
	v_mov_b32_e32 v135, v33
	v_pk_add_f32 v[116:117], v[116:117], v[134:135]
	v_add_f32_e32 v40, v40, v41
	v_add_f32_e32 v40, v40, v117
	v_add_f32_e32 v40, v116, v40
	s_nop 1
	v_add_f32_dpp v40, v40, v40 quad_perm:[1,0,3,2] row_mask:0xf bank_mask:0xf
	s_nop 1
	v_add_f32_dpp v40, v40, v40 quad_perm:[2,3,0,1] row_mask:0xf bank_mask:0xf
	s_nop 1
	v_add_f32_dpp v40, v40, v40 row_half_mirror row_mask:0xf bank_mask:0xf
	s_nop 1
	v_add_f32_dpp v40, v40, v40 row_ror:8 row_mask:0xf bank_mask:0xf
	v_mov_b32_e32 v41, v40
	s_nop 1
	v_permlane16_swap_b32_e32 v41, v40
	v_add_f32_e32 v40, v40, v41
	v_mov_b32_e32 v41, v40
	s_nop 1
	v_permlane32_swap_b32_e32 v41, v40
	v_add_f32_e32 v40, v40, v41
	v_fmamk_f32 v117, v40, 0xbb000000, v39
	v_fmac_f32_e32 v37, 0xbb000000, v40
	v_fmamk_f32 v116, v40, 0xbb000000, v38
	v_fmamk_f32 v36, v40, 0xbb000000, v36
	v_mul_f32_e32 v38, v37, v37
	v_mul_f32_e32 v39, v117, v117
	v_fmamk_f32 v33, v40, 0xbb000000, v33
	v_fmamk_f32 v32, v40, 0xbb000000, v32
	v_fmamk_f32 v35, v40, 0xbb000000, v35
	v_fmac_f32_e32 v34, 0xbb000000, v40
	v_fmac_f32_e32 v38, v36, v36
	v_fmac_f32_e32 v39, v116, v116
	v_add_f32_e32 v118, v38, v39
	v_pk_mul_f32 v[38:39], v[34:35], v[34:35]
	v_pk_mul_f32 v[40:41], v[32:33], v[32:33]
	v_mov_b32_e32 v134, v38
	v_mov_b32_e32 v135, v40
	v_mov_b32_e32 v40, v39
	v_pk_add_f32 v[38:39], v[134:135], v[40:41]
	s_nop 0
	v_add_f32_e32 v39, v39, v118
	v_add_f32_e32 v38, v38, v39
	s_nop 1
	v_add_f32_dpp v38, v38, v38 quad_perm:[1,0,3,2] row_mask:0xf bank_mask:0xf
	s_nop 1
	v_add_f32_dpp v38, v38, v38 quad_perm:[2,3,0,1] row_mask:0xf bank_mask:0xf
	s_nop 1
	v_add_f32_dpp v38, v38, v38 row_half_mirror row_mask:0xf bank_mask:0xf
	s_nop 1
	v_add_f32_dpp v38, v38, v38 row_ror:8 row_mask:0xf bank_mask:0xf
	v_mov_b32_e32 v39, v38
	s_nop 1
	v_permlane16_swap_b32_e32 v39, v38
	v_add_f32_e32 v38, v38, v39
	v_mov_b32_e32 v39, v38
	s_nop 1
	v_permlane32_swap_b32_e32 v39, v38
	v_add_f32_e32 v38, v38, v39
	v_fmamk_f32 v38, v38, 0x3b000000, v131
	v_cmp_gt_f32_e32 vcc, s71, v38
	v_mul_f32_e32 v39, 0x4f800000, v38
	s_nop 0
	v_cndmask_b32_e32 v38, v38, v39, vcc
	v_sqrt_f32_e32 v39, v38
	s_nop 0
	v_add_u32_e32 v40, -1, v39
	v_fma_f32 v41, -v40, v39, v38
	v_cmp_ge_f32_e64 s[0:1], 0, v41
	v_add_u32_e32 v41, 1, v39
	s_nop 0
	v_cndmask_b32_e64 v40, v39, v40, s[0:1]
	v_fma_f32 v39, -v41, v39, v38
	v_cmp_lt_f32_e64 s[0:1], 0, v39
	s_nop 1
	v_cndmask_b32_e64 v39, v40, v41, s[0:1]
	v_mul_f32_e32 v40, 0x37800000, v39
	v_cndmask_b32_e32 v39, v39, v40, vcc
	v_cmp_class_f32_e32 vcc, v38, v132
	s_nop 1
	v_cndmask_b32_e32 v38, v39, v38, vcc
	v_div_scale_f32 v39, s[0:1], v38, v38, 1.0
	v_rcp_f32_e32 v40, v39
	s_add_i32 s0, s8, s16
	s_ashr_i32 s1, s0, 31
	s_lshl_b64 s[0:1], s[0:1], 11
	v_fma_f32 v41, -v39, v40, 1.0
	v_fmac_f32_e32 v40, v41, v40
	v_div_scale_f32 v41, vcc, 1.0, v38, 1.0
	v_mul_f32_e32 v118, v41, v40
	v_fma_f32 v133, -v39, v118, v41
	v_fmac_f32_e32 v118, v133, v40
	v_fma_f32 v39, -v39, v118, v41
	v_div_fmas_f32 v39, v39, v40, v118
	v_div_fixup_f32 v118, v39, v38, 1.0
	s_nop 0
	s_nop 0
	s_nop 0
	s_nop 0
	v_pk_mul_f32 v[36:37], v[36:37], v[118:119] op_sel_hi:[1,0]
	v_pk_mul_f32 v[32:33], v[32:33], v[118:119] op_sel_hi:[1,0]
	v_pk_mul_f32 v[34:35], v[34:35], v[118:119] op_sel_hi:[1,0]
	v_pk_mul_f32 v[116:117], v[116:117], v[118:119] op_sel_hi:[1,0]
	s_andn2_b64 vcc, exec, s[90:91]
	s_nop 0
	v_pk_fma_f32 v[40:41], v[230:231], v[34:35], v[238:239]
	s_nop 0
	v_pk_fma_f32 v[36:37], v[232:233], v[36:37], v[240:241]
	v_pk_fma_f32 v[34:35], v[228:229], v[32:33], v[236:237]
	v_mul_f32_e32 v32, 0xbfb8aa3b, v36
	v_mul_f32_e32 v33, 0xbfb8aa3b, v37
	v_exp_f32_e32 v32, v32
	v_exp_f32_e32 v33, v33
	v_pk_fma_f32 v[116:117], v[234:235], v[116:117], v[242:243]
	v_add_f32_e32 v32, 1.0, v32
	v_add_f32_e32 v33, 1.0, v33
	v_rcp_f32_e32 v32, v32
	v_rcp_f32_e32 v33, v33
	v_mul_f32_e32 v32, v36, v32
	v_mul_f32_e32 v33, v37, v33
	v_cvt_pk_bf16_f32 v32, v32, v33
	v_mul_f32_e32 v33, 0xbfb8aa3b, v116
	v_mul_f32_e32 v36, 0xbfb8aa3b, v117
	v_exp_f32_e32 v33, v33
	v_exp_f32_e32 v36, v36
	v_add_f32_e32 v33, 1.0, v33
	v_add_f32_e32 v36, 1.0, v36
	v_rcp_f32_e32 v33, v33
	v_rcp_f32_e32 v36, v36
	v_mul_f32_e32 v33, v116, v33
	v_mul_f32_e32 v36, v117, v36
	v_cvt_pk_bf16_f32 v33, v33, v36
	v_mul_f32_e32 v36, 0xbfb8aa3b, v34
	v_exp_f32_e32 v36, v36
	s_nop 0
	v_add_f32_e32 v36, 1.0, v36
	v_rcp_f32_e32 v36, v36
	s_nop 0
	v_mul_f32_e32 v34, v34, v36
	v_mul_f32_e32 v36, 0xbfb8aa3b, v35
	v_exp_f32_e32 v36, v36
	s_nop 0
	v_add_f32_e32 v36, 1.0, v36
	v_rcp_f32_e32 v36, v36
	s_nop 0
	v_mul_f32_e32 v35, v35, v36
	v_cvt_pk_bf16_f32 v34, v34, v35
	v_mul_f32_e32 v35, 0xbfb8aa3b, v40
	v_mul_f32_e32 v36, 0xbfb8aa3b, v41
	v_exp_f32_e32 v35, v35
	v_exp_f32_e32 v36, v36
	v_add_f32_e32 v35, 1.0, v35
	v_add_f32_e32 v36, 1.0, v36
	v_rcp_f32_e32 v35, v35
	v_rcp_f32_e32 v36, v36
	v_mul_f32_e32 v35, v40, v35
	v_mul_f32_e32 v36, v41, v36
	v_cvt_pk_bf16_f32 v35, v35, v36
	v_lshl_add_u64 v[36:37], v[114:115], 0, s[0:1]
	global_store_dwordx4 v[36:37], v[32:35], off offset:1024
	s_barrier
	s_cbranch_vccz .LBB0_781

.LBB0_940:
	s_or_b64 exec, exec, s[6:7]
	s_cmpk_gt_u32 s46, 0xff
	ds_write_b32 v63, v0 offset:6144
	s_waitcnt lgkmcnt(0)
	s_barrier
	s_cbranch_scc1 .LBB0_926
	v_lshl_add_u32 v0, s47, 9, v64
	ds_read2st64_b32 v[0:1], v0 offset0:24 offset1:25
	s_or_b32 s6, s47, s14
	s_ashr_i32 s7, s6, 31
	s_lshl_b64 s[46:47], s[6:7], 10
	s_add_u32 s14, s48, s46
	s_waitcnt lgkmcnt(0)
	v_add_f32_e32 v2, v0, v1
	ds_bpermute_b32 v3, v88, v2
	s_addc_u32 s47, s49, s47
	s_lshl_b32 s52, s15, 1
	s_add_u32 s46, s14, s52
	s_addc_u32 s47, s47, 0
	s_waitcnt lgkmcnt(0)
	v_add_f32_e32 v2, v2, v3
	ds_bpermute_b32 v3, v89, v2
	v_lshlrev_b32_e32 v4, 1, v144
	v_or_b32_e32 v7, s15, v144
	global_load_ushort v5, v4, s[46:47]
	global_load_ushort v6, v4, s[46:47] offset:128
	s_waitcnt lgkmcnt(0)
	v_add_f32_e32 v2, v2, v3
	ds_bpermute_b32 v3, v90, v2
	v_lshlrev_b32_e32 v7, 2, v7
	global_load_dword v8, v7, s[60:61]
	s_nop 0
	global_load_dword v7, v7, s[60:61] offset:256
	s_lshl_b64 s[6:7], s[6:7], 11
	s_add_u32 s6, s24, s6
	s_waitcnt lgkmcnt(0)
	v_add_f32_e32 v2, v2, v3
	ds_bpermute_b32 v3, v91, v2
	s_addc_u32 s7, s25, s7
	s_add_u32 s6, s6, s52
	s_addc_u32 s7, s7, 0
	s_waitcnt lgkmcnt(0)
	v_add_f32_e32 v2, v2, v3
	ds_bpermute_b32 v3, v92, v2
	s_waitcnt lgkmcnt(0)
	v_add_f32_e32 v2, v2, v3
	ds_bpermute_b32 v3, v93, v2
	s_waitcnt lgkmcnt(0)
	v_add_f32_e32 v2, v2, v3
	v_fmac_f32_e32 v1, 0xbc000000, v2
	v_fmamk_f32 v0, v2, 0xbc000000, v0
	v_mul_f32_e32 v2, v1, v1
	v_fmac_f32_e32 v2, v0, v0
	s_nop 1
	v_add_f32_dpp v2, v2, v2 quad_perm:[1,0,3,2] row_mask:0xf bank_mask:0xf
	s_nop 1
	v_add_f32_dpp v2, v2, v2 quad_perm:[2,3,0,1] row_mask:0xf bank_mask:0xf
	s_nop 1
	v_add_f32_dpp v2, v2, v2 row_half_mirror row_mask:0xf bank_mask:0xf
	s_nop 1
	v_add_f32_dpp v2, v2, v2 row_ror:8 row_mask:0xf bank_mask:0xf
	v_mov_b32_e32 v3, v2
	s_nop 1
	v_permlane16_swap_b32_e32 v3, v2
	v_add_f32_e32 v2, v2, v3
	v_mov_b32_e32 v3, v2
	s_nop 1
	v_permlane32_swap_b32_e32 v3, v2
	v_add_f32_e32 v2, v2, v3
	v_fmamk_f32 v2, v2, 0x3c000000, v83
	v_mul_f32_e32 v3, 0x4f800000, v2
	v_cmp_gt_f32_e32 vcc, s42, v2
	s_waitcnt vmcnt(3)
	v_lshlrev_b32_e32 v5, 16, v5
	v_cndmask_b32_e32 v2, v2, v3, vcc
	v_sqrt_f32_e32 v3, v2
	s_waitcnt vmcnt(2)
	v_lshlrev_b32_e32 v6, 16, v6
	v_add_u32_e32 v9, -1, v3
	v_add_u32_e32 v10, 1, v3
	v_fma_f32 v11, -v9, v3, v2
	v_fma_f32 v12, -v10, v3, v2
	v_cmp_ge_f32_e64 s[14:15], 0, v11
	s_nop 1
	v_cndmask_b32_e64 v3, v3, v9, s[14:15]
	v_cmp_lt_f32_e64 s[14:15], 0, v12
	s_nop 1
	v_cndmask_b32_e64 v3, v3, v10, s[14:15]
	v_mul_f32_e32 v9, 0x37800000, v3
	v_cndmask_b32_e32 v3, v3, v9, vcc
	v_cmp_class_f32_e32 vcc, v2, v84
	s_nop 1
	v_cndmask_b32_e32 v2, v3, v2, vcc
	v_div_scale_f32 v3, s[14:15], v2, v2, 1.0
	v_rcp_f32_e32 v9, v3
	v_div_scale_f32 v10, vcc, 1.0, v2, 1.0
	v_fma_f32 v11, -v3, v9, 1.0
	v_fmac_f32_e32 v9, v11, v9
	v_mul_f32_e32 v11, v10, v9
	v_fma_f32 v12, -v3, v11, v10
	v_fmac_f32_e32 v11, v12, v9
	v_fma_f32 v3, -v3, v11, v10
	v_div_fmas_f32 v3, v3, v9, v11
	v_div_fixup_f32 v2, v3, v2, 1.0
	v_mul_f32_e32 v0, v0, v2
	s_waitcnt vmcnt(1)
	v_mul_f32_e32 v0, v8, v0
	v_mul_f32_e32 v1, v1, v2
	v_mul_f32_e32 v0, v0, v5
	s_waitcnt vmcnt(0)
	v_mul_f32_e32 v1, v7, v1
	v_cvt_pk_bf16_f32 v0, v0, v51
	v_mul_f32_e32 v1, v1, v6
	global_store_short v4, v0, s[6:7]
	v_cvt_pk_bf16_f32 v0, v1, v51
	global_store_short v4, v0, s[6:7] offset:128
	s_branch .LBB0_926

.LBB0_1146:
	s_waitcnt vmcnt(0)
	v_lshlrev_b32_e32 v96, 16, v42
	v_and_b32_e32 v61, 0xffff0000, v42
	v_lshlrev_b32_e32 v98, 16, v43
	v_and_b32_e32 v99, 0xffff0000, v43
	v_lshlrev_b32_e32 v43, 16, v45
	v_lshlrev_b32_e32 v42, 16, v44
	v_and_b32_e32 v45, 0xffff0000, v45
	v_and_b32_e32 v44, 0xffff0000, v44
	v_lshlrev_b32_e32 v103, 16, v47
	v_lshlrev_b32_e32 v102, 16, v46
	v_and_b32_e32 v47, 0xffff0000, v47
	v_and_b32_e32 v46, 0xffff0000, v46
	v_lshlrev_b32_e32 v94, 16, v40
	v_and_b32_e32 v95, 0xffff0000, v40
	v_pk_mul_f32 v[100:101], v[44:45], v[44:45]
	v_pk_mul_f32 v[104:105], v[46:47], v[46:47]
	v_lshlrev_b32_e32 v108, 16, v41
	v_pk_fma_f32 v[100:101], v[42:43], v[42:43], v[100:101]
	v_pk_fma_f32 v[104:105], v[102:103], v[102:103], v[104:105]
	v_mul_f32_e32 v97, v94, v94
	v_mul_f32_e32 v107, v95, v95
	v_and_b32_e32 v109, 0xffff0000, v41
	v_mul_f32_e32 v40, v108, v108
	v_mov_b32_e32 v106, v96
	v_pk_add_f32 v[100:101], v[100:101], v[100:101] op_sel_hi:[0,1]
	v_pk_add_f32 v[104:105], v[104:105], v[104:105] op_sel_hi:[0,1]
	v_pk_fma_f32 v[40:41], v[108:109], v[108:109], v[40:41] op_sel_hi:[1,1,0]
	v_pk_add_f32 v[106:107], v[96:97], v[106:107]
	v_mul_f32_e32 v40, v61, v61
	v_mul_f32_e32 v100, v98, v98
	v_mul_f32_e32 v104, v99, v99
	v_mul_f32_e32 v110, v96, v96
	v_mov_b32_e32 v111, v107
	v_pk_add_f32 v[40:41], v[110:111], v[40:41]
	v_pk_add_f32 v[100:101], v[100:101], v[104:105]
	s_add_u32 s30, s30, 0x800
	v_pk_add_f32 v[40:41], v[40:41], v[100:101]
	s_addc_u32 s31, s31, 0
	v_add_f32_e32 v40, v40, v41
	s_add_u32 s20, s20, 0x400
	s_addc_u32 s21, s21, 0
	s_cmpk_lg_i32 s30, 0x4000
	s_nop 1
	v_add_f32_dpp v40, v40, v40 quad_perm:[1,0,3,2] row_mask:0xf bank_mask:0xf
	s_nop 1
	v_add_f32_dpp v40, v40, v40 quad_perm:[2,3,0,1] row_mask:0xf bank_mask:0xf
	s_nop 1
	v_add_f32_dpp v40, v40, v40 row_half_mirror row_mask:0xf bank_mask:0xf
	s_nop 1
	v_add_f32_dpp v40, v40, v40 row_ror:8 row_mask:0xf bank_mask:0xf
	v_mov_b32_e32 v41, v40
	s_nop 1
	v_permlane16_swap_b32_e32 v41, v40
	v_add_f32_e32 v40, v40, v41
	v_mov_b32_e32 v41, v40
	s_nop 1
	v_permlane32_swap_b32_e32 v41, v40
	v_add_f32_e32 v40, v40, v41
	v_fmamk_f32 v40, v40, 0x3a800000, v49
	v_mul_f32_e32 v41, 0x4f800000, v40
	v_cmp_gt_f32_e32 vcc, s9, v40
	s_nop 1
	v_cndmask_b32_e32 v40, v40, v41, vcc
	v_sqrt_f32_e32 v41, v40
	s_nop 0
	v_add_u32_e32 v97, -1, v41
	v_fma_f32 v100, -v97, v41, v40
	v_cmp_ge_f32_e64 s[0:1], 0, v100
	v_add_u32_e32 v100, 1, v41
	s_nop 0
	v_cndmask_b32_e64 v97, v41, v97, s[0:1]
	v_fma_f32 v41, -v100, v41, v40
	v_cmp_lt_f32_e64 s[0:1], 0, v41
	s_nop 1
	v_cndmask_b32_e64 v41, v97, v100, s[0:1]
	v_mul_f32_e32 v97, 0x37800000, v41
	v_cndmask_b32_e32 v41, v41, v97, vcc
	v_cmp_class_f32_e32 vcc, v40, v92
	s_nop 1
	v_cndmask_b32_e32 v40, v41, v40, vcc
	v_div_scale_f32 v41, s[0:1], v40, v40, 1.0
	v_rcp_f32_e32 v97, v41
	s_nop 0
	v_fma_f32 v100, -v41, v97, 1.0
	v_fmac_f32_e32 v97, v100, v97
	v_div_scale_f32 v100, vcc, 1.0, v40, 1.0
	v_mul_f32_e32 v101, v100, v97
	v_fma_f32 v104, -v41, v101, v100
	v_fmac_f32_e32 v101, v104, v97
	v_fma_f32 v41, -v41, v101, v100
	v_div_fmas_f32 v41, v41, v97, v101
	v_div_fixup_f32 v100, v41, v40, 1.0
	v_mov_b32_e32 v40, v42
	v_mov_b32_e32 v41, v44
	v_mov_b32_e32 v44, v43
	v_pk_mul_f32 v[40:41], v[100:101], v[40:41] op_sel_hi:[0,1]
	v_pk_mul_f32 v[42:43], v[100:101], v[44:45] op_sel_hi:[0,1]
	v_mov_b32_e32 v44, v102
	v_mov_b32_e32 v45, v46
	v_mov_b32_e32 v46, v103
	v_pk_fma_f32 v[42:43], v[70:71], v[42:43], v[22:23]
	v_pk_fma_f32 v[40:41], v[72:73], v[40:41], v[20:21]
	v_pk_mul_f32 v[44:45], v[100:101], v[44:45] op_sel_hi:[0,1]
	v_pk_mul_f32 v[46:47], v[100:101], v[46:47] op_sel_hi:[0,1]
	v_lshl_add_u64 v[104:105], s[6:7], 1, v[68:69]
	v_pk_fma_f32 v[46:47], v[74:75], v[46:47], v[18:19]
	v_pk_fma_f32 v[44:45], v[76:77], v[44:45], v[16:17]
	v_cvt_pk_bf16_f32 v40, v40, v41
	v_cvt_pk_bf16_f32 v41, v42, v43
	v_mov_b32_e32 v97, v61
	v_cvt_pk_bf16_f32 v42, v44, v45
	v_cvt_pk_bf16_f32 v43, v46, v47
	global_store_dwordx4 v[104:105], v[40:43], off
	v_pk_mul_f32 v[44:45], v[96:97], v[100:101] op_sel_hi:[1,0]
	v_pk_mul_f32 v[46:47], v[98:99], v[100:101] op_sel_hi:[1,0]
	v_pk_mul_f32 v[40:41], v[94:95], v[100:101] op_sel_hi:[1,0]
	v_pk_mul_f32 v[42:43], v[108:109], v[100:101] op_sel_hi:[1,0]
	v_pk_fma_f32 v[40:41], v[80:81], v[40:41], v[28:29]
	v_pk_fma_f32 v[42:43], v[78:79], v[42:43], v[30:31]
	v_pk_fma_f32 v[46:47], v[82:83], v[46:47], v[26:27]
	v_pk_fma_f32 v[44:45], v[84:85], v[44:45], v[24:25]
	v_cvt_pk_bf16_f32 v40, v40, v41
	v_cvt_pk_bf16_f32 v41, v42, v43
	s_nop 0
	v_cvt_pk_bf16_f32 v42, v44, v45
	v_cvt_pk_bf16_f32 v43, v46, v47
	global_store_dwordx4 v[104:105], v[40:43], off offset:1024
	v_mov_b32_e32 v44, v32
	v_mov_b32_e32 v45, v33
	v_mov_b32_e32 v46, v34
	v_mov_b32_e32 v47, v35
	v_mov_b32_e32 v40, v36
	v_mov_b32_e32 v41, v37
	v_mov_b32_e32 v42, v38
	v_mov_b32_e32 v43, v39
	s_cbranch_scc0 .LBB0_1144

.LBB0_1151:
	v_lshl_add_u64 v[32:33], v[22:23], 0, v[48:49]
	v_add_co_u32_e64 v60, s[0:1], s3, v32
	v_lshl_add_u64 v[34:35], v[20:21], 0, v[48:49]
	s_nop 0
	v_addc_co_u32_e64 v61, s[0:1], 0, v33, s[0:1]
	v_add_co_u32_e64 v76, s[0:1], s6, v32
	v_add_co_u32_e32 v34, vcc, 0x4000000, v34
	s_nop 0
	v_addc_co_u32_e64 v77, s[0:1], 0, v33, s[0:1]
	v_add_co_u32_e64 v92, s[0:1], s7, v32
	v_ashrrev_i32_e32 v44, 2, v50
	s_nop 0
	v_addc_co_u32_e64 v93, s[0:1], 0, v33, s[0:1]
	v_add_co_u32_e64 v108, s[0:1], s9, v32
	v_add_u32_e32 v162, 0x4000, v50
	s_nop 0
	v_addc_co_u32_e64 v109, s[0:1], 0, v33, s[0:1]
	v_add_co_u32_e64 v124, s[0:1], s28, v32
	v_addc_co_u32_e32 v35, vcc, 0, v35, vcc
	s_nop 0
	v_addc_co_u32_e64 v125, s[0:1], 0, v33, s[0:1]
	v_add_co_u32_e64 v140, s[0:1], s29, v32
	v_add_u32_e32 v51, 8, v44
	s_nop 0
	v_addc_co_u32_e64 v141, s[0:1], 0, v33, s[0:1]
	v_add_co_u32_e64 v158, s[0:1], s30, v32
	v_ashrrev_i32_e32 v163, 31, v162
	v_add_co_u32_e32 v192, vcc, 0xe600000, v32
	v_addc_co_u32_e64 v159, s[0:1], 0, v33, s[0:1]
	v_mad_i64_i32 v[180:181], s[0:1], v51, s31, v[24:25]
	v_lshlrev_b64 v[182:183], 11, v[162:163]
	v_addc_co_u32_e32 v193, vcc, 0, v33, vcc
	global_load_dwordx4 v[44:47], v[60:61], off
	global_load_dwordx4 v[52:55], v[60:61], off offset:1024
	global_load_dwordx4 v[56:59], v[60:61], off offset:2048
	s_nop 0
	global_load_dwordx4 v[60:63], v[60:61], off offset:3072
	s_nop 0
	global_load_dwordx4 v[64:67], v[76:77], off
	global_load_dwordx4 v[68:71], v[76:77], off offset:1024
	global_load_dwordx4 v[72:75], v[76:77], off offset:2048
	s_nop 0
	global_load_dwordx4 v[76:79], v[76:77], off offset:3072
	s_nop 0
	global_load_dwordx4 v[80:83], v[92:93], off
	global_load_dwordx4 v[84:87], v[92:93], off offset:1024
	global_load_dwordx4 v[88:91], v[92:93], off offset:2048
	s_nop 0
	global_load_dwordx4 v[92:95], v[92:93], off offset:3072
	s_nop 0
	global_load_dwordx4 v[96:99], v[108:109], off
	global_load_dwordx4 v[100:103], v[108:109], off offset:1024
	global_load_dwordx4 v[104:107], v[108:109], off offset:2048
	s_nop 0
	global_load_dwordx4 v[108:111], v[108:109], off offset:3072
	s_nop 0
	global_load_dwordx4 v[112:115], v[124:125], off
	global_load_dwordx4 v[116:119], v[124:125], off offset:1024
	global_load_dwordx4 v[120:123], v[124:125], off offset:2048
	s_nop 0
	global_load_dwordx4 v[124:127], v[124:125], off offset:3072
	s_nop 0
	global_load_dwordx4 v[128:131], v[140:141], off
	global_load_dwordx4 v[132:135], v[140:141], off offset:1024
	global_load_dwordx4 v[136:139], v[140:141], off offset:2048
	s_nop 0
	global_load_dwordx4 v[140:143], v[140:141], off offset:3072
	s_nop 0
	global_load_dwordx4 v[146:149], v[158:159], off
	global_load_dwordx4 v[150:153], v[158:159], off offset:1024
	global_load_dwordx4 v[154:157], v[158:159], off offset:2048
	s_nop 0
	global_load_dwordx4 v[158:161], v[158:159], off offset:3072
	s_nop 0
	global_load_dwordx4 v[162:165], v[34:35], off
	global_load_dwordx4 v[166:169], v[34:35], off offset:1024
	global_load_dwordx4 v[170:173], v[34:35], off offset:2048
	global_load_dwordx4 v[176:179], v[34:35], off offset:3072
	v_lshl_add_u64 v[196:197], v[180:181], 0, s[16:17]
	v_lshl_add_u64 v[198:199], v[180:181], 0, s[20:21]
	v_lshl_add_u64 v[32:33], v[18:19], 0, v[182:183]
	global_load_dwordx4 v[180:183], v[192:193], off
	global_load_dwordx4 v[184:187], v[192:193], off offset:1024
	global_load_dwordx4 v[188:191], v[192:193], off offset:2048
	s_nop 0
	global_load_dwordx4 v[192:195], v[192:193], off offset:3072
	v_lshl_add_u64 v[200:201], v[196:197], 0, v[16:17]
	v_lshl_add_u64 v[202:203], v[198:199], 0, v[16:17]
	v_lshl_add_u64 v[204:205], v[196:197], 0, v[26:27]
	v_lshl_add_u64 v[206:207], v[198:199], 0, v[26:27]
	v_add_u32_e32 v50, s8, v50
	v_lshl_add_u64 v[20:21], v[20:21], 0, s[12:13]
	v_lshl_add_u64 v[22:23], v[22:23], 0, s[12:13]
	s_waitcnt vmcnt(3)
	v_pk_add_f32 v[164:165], v[164:165], v[182:183]
	v_pk_add_f32 v[162:163], v[162:163], v[180:181]
	s_waitcnt vmcnt(2)
	v_pk_add_f32 v[168:169], v[168:169], v[186:187]
	v_pk_add_f32 v[166:167], v[166:167], v[184:185]
	s_waitcnt vmcnt(1)
	v_pk_add_f32 v[172:173], v[172:173], v[190:191]
	v_pk_add_f32 v[170:171], v[170:171], v[188:189]
	s_waitcnt vmcnt(0)
	v_pk_add_f32 v[178:179], v[178:179], v[194:195]
	v_pk_add_f32 v[176:177], v[176:177], v[192:193]
	v_pk_add_f32 v[46:47], v[164:165], v[46:47]
	v_pk_add_f32 v[44:45], v[162:163], v[44:45]
	v_pk_add_f32 v[54:55], v[168:169], v[54:55]
	v_pk_add_f32 v[52:53], v[166:167], v[52:53]
	v_pk_add_f32 v[58:59], v[172:173], v[58:59]
	v_pk_add_f32 v[56:57], v[170:171], v[56:57]
	v_pk_add_f32 v[62:63], v[178:179], v[62:63]
	v_pk_add_f32 v[60:61], v[176:177], v[60:61]
	v_pk_add_f32 v[46:47], v[46:47], v[66:67]
	v_pk_add_f32 v[44:45], v[44:45], v[64:65]
	v_pk_add_f32 v[54:55], v[54:55], v[70:71]
	v_pk_add_f32 v[52:53], v[52:53], v[68:69]
	v_pk_add_f32 v[58:59], v[58:59], v[74:75]
	v_pk_add_f32 v[56:57], v[56:57], v[72:73]
	v_pk_add_f32 v[62:63], v[62:63], v[78:79]
	v_pk_add_f32 v[60:61], v[60:61], v[76:77]
	v_pk_add_f32 v[46:47], v[46:47], v[82:83]
	v_pk_add_f32 v[44:45], v[44:45], v[80:81]
	v_pk_add_f32 v[54:55], v[54:55], v[86:87]
	v_pk_add_f32 v[52:53], v[52:53], v[84:85]
	v_pk_add_f32 v[58:59], v[58:59], v[90:91]
	v_pk_add_f32 v[56:57], v[56:57], v[88:89]
	v_pk_add_f32 v[62:63], v[62:63], v[94:95]
	v_pk_add_f32 v[60:61], v[60:61], v[92:93]
	v_pk_add_f32 v[46:47], v[46:47], v[98:99]
	v_pk_add_f32 v[44:45], v[44:45], v[96:97]
	v_pk_add_f32 v[54:55], v[54:55], v[102:103]
	v_pk_add_f32 v[52:53], v[52:53], v[100:101]
	v_pk_add_f32 v[58:59], v[58:59], v[106:107]
	v_pk_add_f32 v[56:57], v[56:57], v[104:105]
	v_pk_add_f32 v[62:63], v[62:63], v[110:111]
	v_pk_add_f32 v[60:61], v[60:61], v[108:109]
	v_pk_add_f32 v[46:47], v[46:47], v[114:115]
	v_pk_add_f32 v[44:45], v[44:45], v[112:113]
	v_pk_add_f32 v[54:55], v[54:55], v[118:119]
	v_pk_add_f32 v[52:53], v[52:53], v[116:117]
	v_pk_add_f32 v[58:59], v[58:59], v[122:123]
	v_pk_add_f32 v[56:57], v[56:57], v[120:121]
	v_pk_add_f32 v[62:63], v[62:63], v[126:127]
	v_pk_add_f32 v[60:61], v[60:61], v[124:125]
	v_pk_add_f32 v[46:47], v[46:47], v[130:131]
	v_pk_add_f32 v[44:45], v[44:45], v[128:129]
	v_pk_add_f32 v[54:55], v[54:55], v[134:135]
	v_pk_add_f32 v[52:53], v[52:53], v[132:133]
	v_pk_add_f32 v[58:59], v[58:59], v[138:139]
	v_pk_add_f32 v[56:57], v[56:57], v[136:137]
	v_pk_add_f32 v[62:63], v[62:63], v[142:143]
	v_pk_add_f32 v[60:61], v[60:61], v[140:141]
	v_pk_add_f32 v[46:47], v[46:47], v[148:149]
	v_pk_add_f32 v[44:45], v[44:45], v[146:147]
	v_pk_add_f32 v[54:55], v[54:55], v[152:153]
	v_pk_add_f32 v[52:53], v[52:53], v[150:151]
	v_pk_add_f32 v[58:59], v[58:59], v[156:157]
	v_pk_add_f32 v[56:57], v[56:57], v[154:155]
	v_pk_add_f32 v[62:63], v[62:63], v[160:161]
	v_pk_add_f32 v[60:61], v[60:61], v[158:159]
	global_store_dwordx4 v[34:35], v[44:47], off
	global_store_dwordx4 v[34:35], v[52:55], off offset:1024
	global_store_dwordx4 v[34:35], v[56:59], off offset:2048
	global_store_dwordx4 v[34:35], v[60:63], off offset:3072
	v_pk_mul_f32 v[34:35], v[46:47], v[46:47]
	v_pk_mul_f32 v[72:73], v[44:45], v[44:45]
	v_pk_mul_f32 v[64:65], v[54:55], v[54:55]
	v_pk_mul_f32 v[74:75], v[52:53], v[52:53]
	v_mul_f32_e32 v66, v57, v57
	v_mul_f32_e32 v68, v59, v59
	v_pk_mov_b32 v[76:77], v[72:73], v[34:35] op_sel:[1,0]
	v_mov_b32_e32 v73, v35
	v_pk_mov_b32 v[34:35], v[74:75], v[64:65] op_sel:[1,0]
	v_mov_b32_e32 v75, v65
	v_pk_fma_f32 v[78:79], v[56:57], v[56:57], v[66:67] op_sel_hi:[1,1,0]
	v_pk_fma_f32 v[80:81], v[58:59], v[58:59], v[68:69] op_sel_hi:[1,1,0]
	global_load_dwordx4 v[64:67], v[200:201], off
	global_load_dwordx4 v[68:71], v[202:203], off
	v_pk_add_f32 v[72:73], v[76:77], v[72:73]
	v_pk_add_f32 v[34:35], v[34:35], v[74:75]
	v_mul_f32_e32 v51, v60, v60
	v_mul_f32_e32 v82, v61, v61
	v_mul_f32_e32 v83, v62, v62
	v_mul_f32_e32 v84, v63, v63
	v_pk_add_f32 v[72:73], v[72:73], v[72:73] op_sel:[0,1] op_sel_hi:[1,0]
	v_pk_add_f32 v[34:35], v[34:35], v[34:35] op_sel:[0,1] op_sel_hi:[1,0]
	v_mov_b32_e32 v79, v83
	v_mov_b32_e32 v81, v84
	v_mov_b32_e32 v73, v51
	v_mov_b32_e32 v35, v82
	v_pk_add_f32 v[74:75], v[78:79], v[80:81]
	v_pk_add_f32 v[34:35], v[72:73], v[34:35]
	s_waitcnt vmcnt(1)
	v_pk_add_f32 v[64:65], v[64:65], 1.0 op_sel_hi:[1,0]
	v_pk_add_f32 v[34:35], v[34:35], v[74:75]
	v_pk_add_f32 v[66:67], v[66:67], 1.0 op_sel_hi:[1,0]
	v_add_f32_e32 v34, v34, v35
	s_nop 1
	v_add_f32_dpp v34, v34, v34 quad_perm:[1,0,3,2] row_mask:0xf bank_mask:0xf
	s_nop 1
	v_add_f32_dpp v34, v34, v34 quad_perm:[2,3,0,1] row_mask:0xf bank_mask:0xf
	s_nop 1
	v_add_f32_dpp v34, v34, v34 row_half_mirror row_mask:0xf bank_mask:0xf
	s_nop 1
	v_add_f32_dpp v34, v34, v34 row_ror:8 row_mask:0xf bank_mask:0xf
	v_mov_b32_e32 v35, v34
	s_nop 1
	v_permlane16_swap_b32_e32 v35, v34
	v_add_f32_e32 v34, v34, v35
	v_mov_b32_e32 v35, v34
	s_nop 1
	v_permlane32_swap_b32_e32 v35, v34
	v_add_f32_e32 v34, v34, v35
	v_fmamk_f32 v34, v34, 0x3a800000, v42
	v_mul_f32_e32 v35, 0x4f800000, v34
	v_cmp_gt_f32_e32 vcc, s36, v34
	s_nop 1
	v_cndmask_b32_e32 v34, v34, v35, vcc
	v_sqrt_f32_e32 v35, v34
	s_nop 0
	v_add_u32_e32 v51, -1, v35
	v_add_u32_e32 v72, 1, v35
	v_fma_f32 v73, -v51, v35, v34
	v_fma_f32 v74, -v72, v35, v34
	v_cmp_ge_f32_e64 s[0:1], 0, v73
	s_nop 1
	v_cndmask_b32_e64 v35, v35, v51, s[0:1]
	v_cmp_lt_f32_e64 s[0:1], 0, v74
	s_nop 1
	v_cndmask_b32_e64 v35, v35, v72, s[0:1]
	v_mul_f32_e32 v51, 0x37800000, v35
	v_cndmask_b32_e32 v35, v35, v51, vcc
	v_cmp_class_f32_e32 vcc, v34, v43
	s_nop 1
	v_cndmask_b32_e32 v34, v35, v34, vcc
	v_div_scale_f32 v35, s[0:1], v34, v34, 1.0
	v_rcp_f32_e32 v72, v35
	v_div_scale_f32 v51, vcc, 1.0, v34, 1.0
	v_fma_f32 v73, -v35, v72, 1.0
	v_fmac_f32_e32 v72, v73, v72
	v_mul_f32_e32 v73, v51, v72
	v_fma_f32 v74, -v35, v73, v51
	v_fmac_f32_e32 v73, v74, v72
	v_fma_f32 v35, -v35, v73, v51
	v_div_fmas_f32 v35, v35, v72, v73
	v_div_fixup_f32 v34, v35, v34, 1.0
	v_pk_mul_f32 v[44:45], v[44:45], v[34:35] op_sel_hi:[1,0]
	v_pk_mul_f32 v[46:47], v[46:47], v[34:35] op_sel_hi:[1,0]
	v_pk_mul_f32 v[44:45], v[0:1], v[44:45]
	v_pk_mul_f32 v[46:47], v[2:3], v[46:47]
	s_waitcnt vmcnt(0)
	v_pk_fma_f32 v[44:45], v[64:65], v[44:45], v[68:69]
	v_pk_fma_f32 v[46:47], v[66:67], v[46:47], v[70:71]
	v_cvt_pk_bf16_f32 v44, v44, v45
	v_pk_mul_f32 v[52:53], v[52:53], v[34:35] op_sel_hi:[1,0]
	v_cvt_pk_bf16_f32 v45, v46, v47
	global_store_dwordx2 v[32:33], v[44:45], off
	global_load_dwordx4 v[44:47], v[204:205], off
	s_nop 0
	global_load_dwordx4 v[64:67], v[206:207], off
	v_pk_mul_f32 v[54:55], v[54:55], v[34:35] op_sel_hi:[1,0]
	v_pk_mul_f32 v[52:53], v[4:5], v[52:53]
	v_pk_mul_f32 v[54:55], v[6:7], v[54:55]
	v_lshl_add_u64 v[68:69], v[196:197], 0, v[28:29]
	v_lshl_add_u64 v[70:71], v[198:199], 0, v[28:29]
	v_pk_mul_f32 v[56:57], v[56:57], v[34:35] op_sel_hi:[1,0]
	v_pk_mul_f32 v[58:59], v[58:59], v[34:35] op_sel_hi:[1,0]
	v_pk_mul_f32 v[56:57], v[8:9], v[56:57]
	v_pk_mul_f32 v[58:59], v[10:11], v[58:59]
	v_cmp_lt_i32_e32 vcc, s37, v50
	s_or_b64 s[14:15], vcc, s[14:15]
	s_waitcnt vmcnt(1)
	v_pk_add_f32 v[44:45], v[44:45], 1.0 op_sel_hi:[1,0]
	v_pk_add_f32 v[46:47], v[46:47], 1.0 op_sel_hi:[1,0]
	s_waitcnt vmcnt(0)
	v_pk_fma_f32 v[44:45], v[44:45], v[52:53], v[64:65]
	v_pk_fma_f32 v[46:47], v[46:47], v[54:55], v[66:67]
	v_cvt_pk_bf16_f32 v44, v44, v45
	v_lshl_add_u64 v[64:65], v[196:197], 0, v[30:31]
	v_cvt_pk_bf16_f32 v45, v46, v47
	global_store_dwordx2 v[32:33], v[44:45], off offset:512
	global_load_dwordx4 v[44:47], v[68:69], off
	s_nop 0
	global_load_dwordx4 v[52:55], v[70:71], off
	v_lshl_add_u64 v[66:67], v[198:199], 0, v[30:31]
	s_waitcnt vmcnt(1)
	v_pk_add_f32 v[44:45], v[44:45], 1.0 op_sel_hi:[1,0]
	v_pk_add_f32 v[46:47], v[46:47], 1.0 op_sel_hi:[1,0]
	s_waitcnt vmcnt(0)
	v_pk_fma_f32 v[44:45], v[56:57], v[44:45], v[52:53]
	v_pk_fma_f32 v[46:47], v[58:59], v[46:47], v[54:55]
	v_cvt_pk_bf16_f32 v44, v44, v45
	v_pk_mul_f32 v[56:57], v[62:63], v[34:35] op_sel_hi:[1,0]
	v_cvt_pk_bf16_f32 v45, v46, v47
	global_store_dwordx2 v[32:33], v[44:45], off offset:1024
	global_load_dwordx4 v[44:47], v[64:65], off
	s_nop 0
	global_load_dwordx4 v[52:55], v[66:67], off
	v_pk_mul_f32 v[34:35], v[60:61], v[34:35] op_sel_hi:[1,0]
	v_pk_mul_f32 v[56:57], v[14:15], v[56:57]
	v_pk_mul_f32 v[34:35], v[12:13], v[34:35]
	s_waitcnt vmcnt(1)
	v_pk_add_f32 v[44:45], v[44:45], 1.0 op_sel_hi:[1,0]
	v_pk_add_f32 v[46:47], v[46:47], 1.0 op_sel_hi:[1,0]
	s_waitcnt vmcnt(0)
	v_pk_fma_f32 v[34:35], v[34:35], v[44:45], v[52:53]
	v_pk_fma_f32 v[46:47], v[56:57], v[46:47], v[54:55]
	v_cvt_pk_bf16_f32 v34, v34, v35
	s_nop 0
	v_cvt_pk_bf16_f32 v35, v46, v47
	global_store_dwordx2 v[32:33], v[34:35], off offset:1536
	s_andn2_b64 exec, exec, s[14:15]
	s_cbranch_execnz .LBB0_1151

.LBB0_1391:
	s_waitcnt vmcnt(0)
	v_lshlrev_b32_e32 v72, 16, v42
	v_and_b32_e32 v59, 0xffff0000, v42
	v_lshlrev_b32_e32 v74, 16, v43
	v_and_b32_e32 v75, 0xffff0000, v43
	v_lshlrev_b32_e32 v43, 16, v45
	v_lshlrev_b32_e32 v42, 16, v44
	v_and_b32_e32 v45, 0xffff0000, v45
	v_and_b32_e32 v44, 0xffff0000, v44
	v_lshlrev_b32_e32 v79, 16, v47
	v_lshlrev_b32_e32 v78, 16, v46
	v_and_b32_e32 v47, 0xffff0000, v47
	v_and_b32_e32 v46, 0xffff0000, v46
	v_lshlrev_b32_e32 v70, 16, v40
	v_and_b32_e32 v71, 0xffff0000, v40
	v_pk_mul_f32 v[76:77], v[44:45], v[44:45]
	v_pk_mul_f32 v[80:81], v[46:47], v[46:47]
	v_lshlrev_b32_e32 v84, 16, v41
	v_pk_fma_f32 v[76:77], v[42:43], v[42:43], v[76:77]
	v_pk_fma_f32 v[80:81], v[78:79], v[78:79], v[80:81]
	v_mul_f32_e32 v73, v70, v70
	v_mul_f32_e32 v83, v71, v71
	v_and_b32_e32 v85, 0xffff0000, v41
	v_mul_f32_e32 v40, v84, v84
	v_mov_b32_e32 v82, v72
	v_pk_add_f32 v[76:77], v[76:77], v[76:77] op_sel_hi:[0,1]
	v_pk_add_f32 v[80:81], v[80:81], v[80:81] op_sel_hi:[0,1]
	v_pk_fma_f32 v[40:41], v[84:85], v[84:85], v[40:41] op_sel_hi:[1,1,0]
	v_pk_add_f32 v[82:83], v[72:73], v[82:83]
	v_mul_f32_e32 v40, v59, v59
	v_mul_f32_e32 v76, v74, v74
	v_mul_f32_e32 v80, v75, v75
	v_mul_f32_e32 v86, v72, v72
	v_mov_b32_e32 v87, v83
	v_pk_add_f32 v[40:41], v[86:87], v[40:41]
	v_pk_add_f32 v[76:77], v[76:77], v[80:81]
	s_add_u32 s12, s12, 0x800
	v_pk_add_f32 v[40:41], v[40:41], v[76:77]
	s_addc_u32 s13, s13, 0
	v_add_f32_e32 v40, v40, v41
	s_add_u32 s10, s10, 0x400
	s_addc_u32 s11, s11, 0
	s_cmpk_lg_i32 s12, 0x4000
	s_nop 1
	v_add_f32_dpp v40, v40, v40 quad_perm:[1,0,3,2] row_mask:0xf bank_mask:0xf
	s_nop 1
	v_add_f32_dpp v40, v40, v40 quad_perm:[2,3,0,1] row_mask:0xf bank_mask:0xf
	s_nop 1
	v_add_f32_dpp v40, v40, v40 row_half_mirror row_mask:0xf bank_mask:0xf
	s_nop 1
	v_add_f32_dpp v40, v40, v40 row_ror:8 row_mask:0xf bank_mask:0xf
	v_mov_b32_e32 v41, v40
	s_nop 1
	v_permlane16_swap_b32_e32 v41, v40
	v_add_f32_e32 v40, v40, v41
	v_mov_b32_e32 v41, v40
	s_nop 1
	v_permlane32_swap_b32_e32 v41, v40
	v_add_f32_e32 v40, v40, v41
	v_fmamk_f32 v40, v40, 0x3a800000, v68
	v_mul_f32_e32 v41, 0x4f800000, v40
	v_cmp_gt_f32_e32 vcc, s3, v40
	s_nop 1
	v_cndmask_b32_e32 v40, v40, v41, vcc
	v_sqrt_f32_e32 v41, v40
	s_nop 0
	v_add_u32_e32 v73, -1, v41
	v_fma_f32 v76, -v73, v41, v40
	v_cmp_ge_f32_e64 s[0:1], 0, v76
	v_add_u32_e32 v76, 1, v41
	s_nop 0
	v_cndmask_b32_e64 v73, v41, v73, s[0:1]
	v_fma_f32 v41, -v76, v41, v40
	v_cmp_lt_f32_e64 s[0:1], 0, v41
	s_nop 1
	v_cndmask_b32_e64 v41, v73, v76, s[0:1]
	v_mul_f32_e32 v73, 0x37800000, v41
	v_cndmask_b32_e32 v41, v41, v73, vcc
	v_cmp_class_f32_e32 vcc, v40, v69
	s_nop 1
	v_cndmask_b32_e32 v40, v41, v40, vcc
	v_div_scale_f32 v41, s[0:1], v40, v40, 1.0
	v_rcp_f32_e32 v73, v41
	s_nop 0
	v_fma_f32 v76, -v41, v73, 1.0
	v_fmac_f32_e32 v73, v76, v73
	v_div_scale_f32 v76, vcc, 1.0, v40, 1.0
	v_mul_f32_e32 v77, v76, v73
	v_fma_f32 v80, -v41, v77, v76
	v_fmac_f32_e32 v77, v80, v73
	v_fma_f32 v41, -v41, v77, v76
	v_div_fmas_f32 v41, v41, v73, v77
	v_div_fixup_f32 v76, v41, v40, 1.0
	v_mov_b32_e32 v40, v42
	v_mov_b32_e32 v41, v44
	v_mov_b32_e32 v44, v43
	v_pk_mul_f32 v[40:41], v[76:77], v[40:41] op_sel_hi:[0,1]
	v_pk_mul_f32 v[42:43], v[76:77], v[44:45] op_sel_hi:[0,1]
	v_lshl_add_u64 v[80:81], s[14:15], 2, v[60:61]
	v_pk_mul_f32 v[42:43], v[22:23], v[42:43]
	v_pk_mul_f32 v[40:41], v[20:21], v[40:41]
	global_store_dwordx4 v[80:81], v[40:43], off
	v_mov_b32_e32 v73, v59
	v_mov_b32_e32 v44, v32
	v_mov_b32_e32 v40, v78
	v_mov_b32_e32 v41, v46
	v_mov_b32_e32 v46, v79
	v_pk_mul_f32 v[40:41], v[76:77], v[40:41] op_sel_hi:[0,1]
	v_pk_mul_f32 v[42:43], v[76:77], v[46:47] op_sel_hi:[0,1]
	v_pk_mul_f32 v[42:43], v[18:19], v[42:43]
	v_pk_mul_f32 v[40:41], v[16:17], v[40:41]
	global_store_dwordx4 v[80:81], v[40:43], off offset:16
	v_mov_b32_e32 v45, v33
	v_mov_b32_e32 v46, v34
	v_pk_mul_f32 v[40:41], v[70:71], v[76:77] op_sel_hi:[1,0]
	v_pk_mul_f32 v[42:43], v[84:85], v[76:77] op_sel_hi:[1,0]
	v_pk_mul_f32 v[40:41], v[28:29], v[40:41]
	v_pk_mul_f32 v[42:43], v[30:31], v[42:43]
	global_store_dwordx4 v[80:81], v[40:43], off offset:2048
	v_mov_b32_e32 v47, v35
	s_nop 0
	v_pk_mul_f32 v[40:41], v[72:73], v[76:77] op_sel_hi:[1,0]
	v_pk_mul_f32 v[42:43], v[74:75], v[76:77] op_sel_hi:[1,0]
	v_pk_mul_f32 v[40:41], v[24:25], v[40:41]
	v_pk_mul_f32 v[42:43], v[26:27], v[42:43]
	global_store_dwordx4 v[80:81], v[40:43], off offset:2064
	s_nop 1
	v_mov_b32_e32 v40, v36
	v_mov_b32_e32 v41, v37
	v_mov_b32_e32 v42, v38
	v_mov_b32_e32 v43, v39
	s_cbranch_scc0 .LBB0_1389

.LBB0_1396:
	v_lshl_add_u64 v[22:23], v[16:17], 0, v[48:49]
	v_add_co_u32_e64 v108, s[0:1], s3, v22
	v_add_co_u32_e32 v224, vcc, 0xe600000, v22
	s_nop 0
	v_addc_co_u32_e64 v109, s[0:1], 0, v23, s[0:1]
	v_add_co_u32_e64 v110, s[0:1], s8, v22
	v_lshl_add_u64 v[20:21], v[18:19], 0, v[48:49]
	s_nop 0
	v_addc_co_u32_e64 v111, s[0:1], 0, v23, s[0:1]
	v_add_co_u32_e64 v112, s[0:1], s9, v22
	v_addc_co_u32_e32 v225, vcc, 0, v23, vcc
	s_nop 0
	v_addc_co_u32_e64 v113, s[0:1], 0, v23, s[0:1]
	v_add_co_u32_e64 v114, s[0:1], s10, v22
	global_load_dwordx4 v[32:35], v[20:21], off
	global_load_dwordx4 v[36:39], v[20:21], off offset:1024
	global_load_dwordx4 v[40:43], v[20:21], off offset:2048
	global_load_dwordx4 v[44:47], v[20:21], off offset:3072
	v_addc_co_u32_e64 v115, s[0:1], 0, v23, s[0:1]
	v_add_co_u32_e64 v128, s[0:1], s11, v22
	v_add_u32_e32 v50, s2, v50
	s_nop 0
	v_addc_co_u32_e64 v129, s[0:1], 0, v23, s[0:1]
	v_add_co_u32_e64 v144, s[0:1], s12, v22
	v_lshl_add_u64 v[16:17], v[16:17], 0, s[4:5]
	s_nop 0
	v_addc_co_u32_e64 v145, s[0:1], 0, v23, s[0:1]
	v_add_co_u32_e64 v160, s[0:1], s13, v22
	v_lshl_add_u64 v[18:19], v[18:19], 0, s[4:5]
	s_nop 0
	v_addc_co_u32_e64 v161, s[0:1], 0, v23, s[0:1]
	v_add_co_u32_e64 v176, s[0:1], s14, v22
	s_nop 1
	v_addc_co_u32_e64 v177, s[0:1], 0, v23, s[0:1]
	v_add_co_u32_e64 v192, s[0:1], s15, v22
	s_nop 1
	v_addc_co_u32_e64 v193, s[0:1], 0, v23, s[0:1]
	v_add_co_u32_e64 v208, s[0:1], s16, v22
	s_nop 1
	v_addc_co_u32_e64 v209, s[0:1], 0, v23, s[0:1]
	global_load_dwordx4 v[52:55], v[108:109], off
	global_load_dwordx4 v[56:59], v[108:109], off offset:1024
	global_load_dwordx4 v[60:63], v[108:109], off offset:2048
	global_load_dwordx4 v[64:67], v[108:109], off offset:3072
	global_load_dwordx4 v[68:71], v[110:111], off
	global_load_dwordx4 v[72:75], v[110:111], off offset:1024
	global_load_dwordx4 v[76:79], v[110:111], off offset:2048
	global_load_dwordx4 v[80:83], v[110:111], off offset:3072
	global_load_dwordx4 v[84:87], v[112:113], off
	global_load_dwordx4 v[88:91], v[112:113], off offset:1024
	global_load_dwordx4 v[92:95], v[112:113], off offset:2048
	global_load_dwordx4 v[96:99], v[112:113], off offset:3072
	global_load_dwordx4 v[100:103], v[114:115], off
	global_load_dwordx4 v[104:107], v[114:115], off offset:1024
	global_load_dwordx4 v[108:111], v[114:115], off offset:2048
	s_nop 0
	global_load_dwordx4 v[112:115], v[114:115], off offset:3072
	s_nop 0
	global_load_dwordx4 v[116:119], v[128:129], off
	global_load_dwordx4 v[120:123], v[128:129], off offset:1024
	global_load_dwordx4 v[124:127], v[128:129], off offset:2048
	s_nop 0
	global_load_dwordx4 v[128:131], v[128:129], off offset:3072
	s_nop 0
	global_load_dwordx4 v[132:135], v[144:145], off
	global_load_dwordx4 v[136:139], v[144:145], off offset:1024
	global_load_dwordx4 v[140:143], v[144:145], off offset:2048
	s_nop 0
	global_load_dwordx4 v[144:147], v[144:145], off offset:3072
	s_nop 0
	global_load_dwordx4 v[148:151], v[160:161], off
	global_load_dwordx4 v[152:155], v[160:161], off offset:1024
	global_load_dwordx4 v[156:159], v[160:161], off offset:2048
	s_nop 0
	global_load_dwordx4 v[160:163], v[160:161], off offset:3072
	s_nop 0
	global_load_dwordx4 v[164:167], v[176:177], off
	global_load_dwordx4 v[168:171], v[176:177], off offset:1024
	global_load_dwordx4 v[172:175], v[176:177], off offset:2048
	s_nop 0
	global_load_dwordx4 v[176:179], v[176:177], off offset:3072
	s_nop 0
	global_load_dwordx4 v[180:183], v[192:193], off
	global_load_dwordx4 v[184:187], v[192:193], off offset:1024
	global_load_dwordx4 v[188:191], v[192:193], off offset:2048
	s_nop 0
	global_load_dwordx4 v[192:195], v[192:193], off offset:3072
	s_nop 0
	s_nop 0
	s_nop 0
	global_load_dwordx4 v[212:215], v[224:225], off
	global_load_dwordx4 v[216:219], v[224:225], off offset:1024
	global_load_dwordx4 v[220:223], v[224:225], off offset:2048
	s_nop 0
	global_load_dwordx4 v[224:227], v[224:225], off offset:3072
	v_cmp_lt_i32_e64 s[0:1], s17, v50
	s_or_b64 s[6:7], s[0:1], s[6:7]
	s_waitcnt vmcnt(3)
	v_pk_add_f32 v[22:23], v[34:35], v[214:215]
	v_pk_add_f32 v[32:33], v[32:33], v[212:213]
	s_waitcnt vmcnt(2)
	v_pk_add_f32 v[34:35], v[38:39], v[218:219]
	v_pk_add_f32 v[36:37], v[36:37], v[216:217]
	v_pk_add_f32 v[22:23], v[22:23], v[54:55]
	v_pk_add_f32 v[32:33], v[32:33], v[52:53]
	v_pk_add_f32 v[34:35], v[34:35], v[58:59]
	v_pk_add_f32 v[36:37], v[36:37], v[56:57]
	s_waitcnt vmcnt(1)
	v_pk_add_f32 v[38:39], v[42:43], v[222:223]
	v_pk_add_f32 v[40:41], v[40:41], v[220:221]
	s_waitcnt vmcnt(0)
	v_pk_add_f32 v[44:45], v[44:45], v[224:225]
	v_pk_add_f32 v[22:23], v[22:23], v[70:71]
	v_pk_add_f32 v[32:33], v[32:33], v[68:69]
	v_pk_add_f32 v[34:35], v[34:35], v[74:75]
	v_pk_add_f32 v[36:37], v[36:37], v[72:73]
	v_pk_add_f32 v[42:43], v[46:47], v[226:227]
	v_pk_add_f32 v[38:39], v[38:39], v[62:63]
	v_pk_add_f32 v[40:41], v[40:41], v[60:61]
	v_pk_add_f32 v[44:45], v[44:45], v[64:65]
	v_pk_add_f32 v[22:23], v[22:23], v[86:87]
	v_pk_add_f32 v[32:33], v[32:33], v[84:85]
	v_pk_add_f32 v[34:35], v[34:35], v[90:91]
	v_pk_add_f32 v[36:37], v[36:37], v[88:89]
	v_pk_add_f32 v[42:43], v[42:43], v[66:67]
	v_pk_add_f32 v[38:39], v[38:39], v[78:79]
	v_pk_add_f32 v[40:41], v[40:41], v[76:77]
	v_pk_add_f32 v[44:45], v[44:45], v[80:81]
	v_pk_add_f32 v[22:23], v[22:23], v[102:103]
	v_pk_add_f32 v[32:33], v[32:33], v[100:101]
	v_pk_add_f32 v[34:35], v[34:35], v[106:107]
	v_pk_add_f32 v[36:37], v[36:37], v[104:105]
	v_pk_add_f32 v[42:43], v[42:43], v[82:83]
	v_pk_add_f32 v[38:39], v[38:39], v[94:95]
	v_pk_add_f32 v[40:41], v[40:41], v[92:93]
	v_pk_add_f32 v[44:45], v[44:45], v[96:97]
	v_pk_add_f32 v[22:23], v[22:23], v[118:119]
	v_pk_add_f32 v[32:33], v[32:33], v[116:117]
	v_pk_add_f32 v[34:35], v[34:35], v[122:123]
	v_pk_add_f32 v[36:37], v[36:37], v[120:121]
	v_pk_add_f32 v[42:43], v[42:43], v[98:99]
	v_pk_add_f32 v[38:39], v[38:39], v[110:111]
	v_pk_add_f32 v[40:41], v[40:41], v[108:109]
	v_pk_add_f32 v[44:45], v[44:45], v[112:113]
	v_pk_add_f32 v[22:23], v[22:23], v[134:135]
	v_pk_add_f32 v[32:33], v[32:33], v[132:133]
	v_pk_add_f32 v[34:35], v[34:35], v[138:139]
	v_pk_add_f32 v[36:37], v[36:37], v[136:137]
	v_pk_add_f32 v[42:43], v[42:43], v[114:115]
	v_pk_add_f32 v[38:39], v[38:39], v[126:127]
	v_pk_add_f32 v[40:41], v[40:41], v[124:125]
	v_pk_add_f32 v[44:45], v[44:45], v[128:129]
	v_pk_add_f32 v[22:23], v[22:23], v[150:151]
	v_pk_add_f32 v[32:33], v[32:33], v[148:149]
	v_pk_add_f32 v[34:35], v[34:35], v[154:155]
	v_pk_add_f32 v[36:37], v[36:37], v[152:153]
	v_pk_add_f32 v[42:43], v[42:43], v[130:131]
	v_pk_add_f32 v[38:39], v[38:39], v[142:143]
	v_pk_add_f32 v[40:41], v[40:41], v[140:141]
	v_pk_add_f32 v[44:45], v[44:45], v[144:145]
	v_pk_add_f32 v[22:23], v[22:23], v[166:167]
	v_pk_add_f32 v[32:33], v[32:33], v[164:165]
	v_pk_add_f32 v[34:35], v[34:35], v[170:171]
	v_pk_add_f32 v[36:37], v[36:37], v[168:169]
	v_pk_add_f32 v[42:43], v[42:43], v[146:147]
	v_pk_add_f32 v[38:39], v[38:39], v[158:159]
	v_pk_add_f32 v[40:41], v[40:41], v[156:157]
	v_pk_add_f32 v[44:45], v[44:45], v[160:161]
	v_pk_add_f32 v[22:23], v[22:23], v[182:183]
	v_pk_add_f32 v[32:33], v[32:33], v[180:181]
	v_pk_add_f32 v[34:35], v[34:35], v[186:187]
	v_pk_add_f32 v[36:37], v[36:37], v[184:185]
	v_pk_add_f32 v[42:43], v[42:43], v[162:163]
	v_pk_add_f32 v[38:39], v[38:39], v[174:175]
	v_pk_add_f32 v[40:41], v[40:41], v[172:173]
	v_pk_add_f32 v[44:45], v[44:45], v[176:177]
	v_pk_add_f32 v[42:43], v[42:43], v[178:179]
	v_pk_add_f32 v[38:39], v[38:39], v[190:191]
	v_pk_add_f32 v[40:41], v[40:41], v[188:189]
	v_pk_add_f32 v[44:45], v[44:45], v[192:193]
	v_pk_mul_f32 v[46:47], v[22:23], v[22:23]
	v_pk_mul_f32 v[52:53], v[32:33], v[32:33]
	v_pk_mul_f32 v[54:55], v[34:35], v[34:35]
	v_pk_mul_f32 v[56:57], v[36:37], v[36:37]
	v_pk_add_f32 v[42:43], v[42:43], v[194:195]
	v_pk_mov_b32 v[62:63], v[52:53], v[46:47] op_sel:[1,0]
	v_mov_b32_e32 v53, v47
	v_pk_mov_b32 v[46:47], v[56:57], v[54:55] op_sel:[1,0]
	v_mov_b32_e32 v57, v55
	v_mul_f32_e32 v61, v45, v45
	v_mul_f32_e32 v58, v41, v41
	v_mul_f32_e32 v60, v39, v39
	v_pk_add_f32 v[52:53], v[62:63], v[52:53]
	v_pk_add_f32 v[46:47], v[46:47], v[56:57]
	v_mul_f32_e32 v51, v44, v44
	v_mul_f32_e32 v64, v42, v42
	v_mul_f32_e32 v65, v43, v43
	v_pk_fma_f32 v[54:55], v[40:41], v[40:41], v[58:59] op_sel_hi:[1,1,0]
	v_pk_fma_f32 v[58:59], v[38:39], v[38:39], v[60:61] op_sel_hi:[1,1,0]
	v_pk_add_f32 v[52:53], v[52:53], v[52:53] op_sel:[0,1] op_sel_hi:[1,0]
	v_pk_add_f32 v[46:47], v[46:47], v[46:47] op_sel:[0,1] op_sel_hi:[1,0]
	v_mov_b32_e32 v55, v64
	v_mov_b32_e32 v59, v65
	v_mov_b32_e32 v53, v51
	v_mov_b32_e32 v47, v61
	v_pk_add_f32 v[54:55], v[54:55], v[58:59]
	v_pk_add_f32 v[46:47], v[52:53], v[46:47]
	s_nop 0
	v_pk_add_f32 v[46:47], v[46:47], v[54:55]
	s_nop 0
	v_add_f32_e32 v46, v46, v47
	s_nop 1
	v_add_f32_dpp v46, v46, v46 quad_perm:[1,0,3,2] row_mask:0xf bank_mask:0xf
	s_nop 1
	v_add_f32_dpp v46, v46, v46 quad_perm:[2,3,0,1] row_mask:0xf bank_mask:0xf
	s_nop 1
	v_add_f32_dpp v46, v46, v46 row_half_mirror row_mask:0xf bank_mask:0xf
	s_nop 1
	v_add_f32_dpp v46, v46, v46 row_ror:8 row_mask:0xf bank_mask:0xf
	v_mov_b32_e32 v47, v46
	s_nop 1
	v_permlane16_swap_b32_e32 v47, v46
	v_add_f32_e32 v46, v46, v47
	v_mov_b32_e32 v47, v46
	s_nop 1
	v_permlane32_swap_b32_e32 v47, v46
	v_add_f32_e32 v46, v46, v47
	v_fmamk_f32 v46, v46, 0x3a800000, v30
	v_mul_f32_e32 v47, 0x4f800000, v46
	v_cmp_gt_f32_e32 vcc, s15, v46
	s_nop 1
	v_cndmask_b32_e32 v46, v46, v47, vcc
	v_sqrt_f32_e32 v47, v46
	s_nop 0
	v_add_u32_e32 v51, -1, v47
	v_add_u32_e32 v52, 1, v47
	v_fma_f32 v53, -v51, v47, v46
	v_fma_f32 v54, -v52, v47, v46
	v_cmp_ge_f32_e64 s[0:1], 0, v53
	s_nop 1
	v_cndmask_b32_e64 v47, v47, v51, s[0:1]
	v_cmp_lt_f32_e64 s[0:1], 0, v54
	s_nop 1
	v_cndmask_b32_e64 v47, v47, v52, s[0:1]
	v_mul_f32_e32 v51, 0x37800000, v47
	v_cndmask_b32_e32 v47, v47, v51, vcc
	v_cmp_class_f32_e32 vcc, v46, v31
	s_nop 1
	v_cndmask_b32_e32 v46, v47, v46, vcc
	v_div_scale_f32 v47, s[0:1], v46, v46, 1.0
	v_rcp_f32_e32 v52, v47
	v_div_scale_f32 v51, vcc, 1.0, v46, 1.0
	v_fma_f32 v53, -v47, v52, 1.0
	v_fmac_f32_e32 v52, v53, v52
	v_mul_f32_e32 v53, v51, v52
	v_fma_f32 v54, -v47, v53, v51
	v_fmac_f32_e32 v53, v54, v52
	v_fma_f32 v47, -v47, v53, v51
	v_div_fmas_f32 v47, v47, v52, v53
	v_div_fixup_f32 v46, v47, v46, 1.0
	v_pk_mul_f32 v[32:33], v[32:33], v[46:47] op_sel_hi:[1,0]
	v_pk_mul_f32 v[22:23], v[22:23], v[46:47] op_sel_hi:[1,0]
	v_pk_mul_f32 v[36:37], v[36:37], v[46:47] op_sel_hi:[1,0]
	v_pk_mul_f32 v[52:53], v[34:35], v[46:47] op_sel_hi:[1,0]
	v_pk_mul_f32 v[40:41], v[40:41], v[46:47] op_sel_hi:[1,0]
	v_pk_mul_f32 v[54:55], v[38:39], v[46:47] op_sel_hi:[1,0]
	v_pk_mul_f32 v[44:45], v[44:45], v[46:47] op_sel_hi:[1,0]
	v_pk_mul_f32 v[46:47], v[42:43], v[46:47] op_sel_hi:[1,0]
	v_pk_mul_f32 v[34:35], v[2:3], v[22:23]
	v_pk_mul_f32 v[32:33], v[0:1], v[32:33]
	v_pk_mul_f32 v[38:39], v[6:7], v[52:53]
	v_pk_mul_f32 v[36:37], v[4:5], v[36:37]
	v_pk_mul_f32 v[42:43], v[10:11], v[54:55]
	v_pk_mul_f32 v[40:41], v[8:9], v[40:41]
	v_pk_mul_f32 v[46:47], v[14:15], v[46:47]
	v_pk_mul_f32 v[44:45], v[12:13], v[44:45]
	global_store_dwordx4 v[20:21], v[32:35], off
	global_store_dwordx4 v[20:21], v[36:39], off offset:1024
	global_store_dwordx4 v[20:21], v[40:43], off offset:2048
	global_store_dwordx4 v[20:21], v[44:47], off offset:3072
	s_andn2_b64 exec, exec, s[6:7]
	s_cbranch_execnz .LBB0_1396
